# E2 loops: back-edge vmcnt(0) + register-rotation moves deferred/counted (RG: vmcnt(20) + deferred second half via s101 flag; GLA: decay scalars land in v209/v242, homed at chunk-B flush point; counted
# speedup vs baseline: 1.0140x; 1.0140x over previous
; __device__ __forceinline__ void rglru_unit(const Params& p, const WS& ws, int j, int u, bool dry = false) {
;     ...
;   float ba[2][4], bx[2][4], sp[2][4];
; #pragma unroll
;   for (int mt = 0; mt < 2; ++mt)
; #pragma unroll
;     for (int jj = 0; jj < 4; ++jj) {
;       const int ch = j * 1024 + 128 * g + 32 * jq + 16 * mt + 4 * lq + jj;
;       ba[mt][jj] = p.ab_gate_a_b[ch]; bx[mt][jj] = p.ab_gate_x_b[ch];
;       sp[mt][jj] = 8.f * log1pf(__expf(-p.ab_lam[ch]));
;     }
.LBB0_1375:
	s_or_b64 exec, exec, s[6:7]
	s_waitcnt vmcnt(1)
	v_mul_f32_e32 v13, 0xbfb8aa3b, v56
	v_exp_f32_e32 v13, v13
	s_mov_b32 s3, 0x3f2aaaab
	s_mov_b32 s10, 0x3f317218
	s_mov_b32 s11, 0x33800000
	v_add_f32_e32 v15, 1.0, v13
	v_add_f32_e32 v56, -1.0, v15
	v_sub_f32_e32 v67, v56, v15
	v_frexp_mant_f32_e32 v63, v15
	v_cvt_f64_f32_e32 v[70:71], v15
	v_sub_f32_e32 v56, v13, v56
	v_add_f32_e32 v67, 1.0, v67
	v_add_f32_e32 v56, v56, v67
	v_frexp_exp_i32_f64_e32 v67, v[70:71]
	v_cmp_gt_f32_e32 vcc, s3, v63
	s_lshl_b32 s92, s9, 1
	s_movk_i32 s9, 0x84
	v_subbrev_co_u32_e32 v63, vcc, 0, v67, vcc
	v_sub_u32_e32 v67, 0, v63
	v_ldexp_f32 v15, v15, v67
	v_ldexp_f32 v56, v56, v67
	v_add_f32_e32 v67, -1.0, v15
	v_add_f32_e32 v71, 1.0, v15
	v_add_f32_e32 v69, 1.0, v67
	v_add_f32_e32 v72, -1.0, v71
	v_sub_f32_e32 v69, v15, v69
	v_sub_f32_e32 v15, v15, v72
	v_add_f32_e32 v15, v56, v15
	v_add_f32_e32 v69, v56, v69
	v_add_f32_e32 v56, v71, v15
	v_rcp_f32_e32 v72, v56
	v_add_f32_e32 v70, v67, v69
	v_sub_f32_e32 v67, v70, v67
	v_sub_f32_e32 v67, v69, v67
	v_sub_f32_e32 v69, v56, v71
	v_sub_f32_e32 v15, v15, v69
	v_mul_f32_e32 v69, v70, v72
	v_mul_f32_e32 v71, v56, v69
	v_fma_f32 v73, v69, v56, -v71
	v_fmac_f32_e32 v73, v69, v15
	v_add_f32_e32 v74, v71, v73
	v_sub_f32_e32 v75, v70, v74
	v_sub_f32_e32 v70, v70, v75
	v_sub_f32_e32 v71, v74, v71
	v_sub_f32_e32 v70, v70, v74
	v_add_f32_e32 v67, v67, v70
	v_sub_f32_e32 v70, v71, v73
	v_add_f32_e32 v67, v70, v67
	v_add_f32_e32 v70, v75, v67
	v_mul_f32_e32 v71, v72, v70
	v_mul_f32_e32 v73, v56, v71
	v_fma_f32 v56, v71, v56, -v73
	v_fmac_f32_e32 v56, v71, v15
	v_sub_f32_e32 v15, v75, v70
	v_add_f32_e32 v15, v67, v15
	v_add_f32_e32 v67, v73, v56
	v_sub_f32_e32 v74, v70, v67
	v_sub_f32_e32 v70, v70, v74
	v_sub_f32_e32 v73, v67, v73
	v_sub_f32_e32 v67, v70, v67
	v_add_f32_e32 v15, v15, v67
	v_sub_f32_e32 v56, v73, v56
	v_cvt_f32_i32_e32 v63, v63
	v_add_f32_e32 v15, v56, v15
	v_add_f32_e32 v56, v69, v71
	v_add_f32_e32 v15, v74, v15
	v_sub_f32_e32 v67, v56, v69
	v_mul_f32_e32 v15, v72, v15
	v_sub_f32_e32 v67, v71, v67
	v_add_f32_e32 v15, v67, v15
	v_mul_f32_e32 v71, 0x3f317218, v63
	v_add_f32_e32 v67, v56, v15
	v_fma_f32 v72, v63, s10, -v71
	v_mul_f32_e32 v69, v67, v67
	v_fmac_f32_e32 v72, 0xb102e308, v63
	v_sub_f32_e32 v56, v67, v56
	v_fmamk_f32 v70, v69, 0x3e9b6dac, v192
	v_sub_f32_e32 v15, v15, v56
	v_add_f32_e32 v56, v71, v72
	v_fmaak_f32 v70, v69, v70, 0x3f2aaada
	v_sub_f32_e32 v63, v56, v71
	v_ldexp_f32 v71, v67, 1
	v_mul_f32_e32 v67, v67, v69
	v_mul_f32_e32 v67, v67, v70
	v_add_f32_e32 v69, v71, v67
	v_sub_f32_e32 v70, v69, v71
	v_ldexp_f32 v15, v15, 1
	v_sub_f32_e32 v67, v67, v70
	v_add_f32_e32 v15, v15, v67
	v_add_f32_e32 v67, v69, v15
	v_sub_f32_e32 v69, v67, v69
	v_sub_f32_e32 v15, v15, v69
	v_add_f32_e32 v69, v56, v67
	v_sub_f32_e32 v70, v69, v56
	v_sub_f32_e32 v71, v69, v70
	v_sub_f32_e32 v63, v72, v63
	v_sub_f32_e32 v56, v56, v71
	v_sub_f32_e32 v67, v67, v70
	v_add_f32_e32 v56, v67, v56
	v_add_f32_e32 v67, v63, v15
	v_sub_f32_e32 v70, v67, v63
	v_sub_f32_e32 v71, v67, v70
	v_sub_f32_e32 v63, v63, v71
	v_sub_f32_e32 v15, v15, v70
	v_add_f32_e32 v56, v67, v56
	v_add_f32_e32 v15, v15, v63
	v_add_f32_e32 v63, v69, v56
	v_sub_f32_e32 v67, v63, v69
	v_sub_f32_e32 v56, v56, v67
	v_add_f32_e32 v15, v15, v56
	v_add_f32_e32 v15, v63, v15
	v_cmp_neq_f32_e32 vcc, s21, v13
	v_mul_f32_e32 v56, 0xbfb8aa3b, v57
	v_exp_f32_e32 v63, v56
	v_cndmask_b32_e32 v15, v199, v15, vcc
	v_cmp_ngt_f32_e32 vcc, -1.0, v13
	s_mov_b32 s6, 0
	s_mov_b32 s7, 1
	v_cndmask_b32_e32 v15, v200, v15, vcc
	v_cmp_neq_f32_e32 vcc, -1.0, v13
	v_lshl_add_u32 v115, v60, 2, s8
	v_cmp_lt_i32_e64 s[38:39], 1, v66
	v_cndmask_b32_e32 v15, v194, v15, vcc
	v_cmp_lt_f32_e64 vcc, |v13|, s11
	v_cmp_lt_i32_e64 s[40:41], 2, v66
	v_cmp_lt_i32_e64 s[42:43], 3, v66
	v_cndmask_b32_e32 v13, v15, v13, vcc
	v_mul_f32_e32 v89, 0x41000000, v13
	v_add_f32_e32 v13, 1.0, v63
	v_add_f32_e32 v15, -1.0, v13
	v_sub_f32_e32 v56, v15, v13
	v_add_f32_e32 v56, 1.0, v56
	v_sub_f32_e32 v15, v63, v15
	v_add_f32_e32 v15, v15, v56
	v_frexp_mant_f32_e32 v67, v13
	v_cvt_f64_f32_e32 v[56:57], v13
	v_frexp_exp_i32_f64_e32 v56, v[56:57]
	v_cmp_gt_f32_e32 vcc, s3, v67
	v_cmp_lt_i32_e64 s[44:45], 4, v66
	v_cmp_lt_i32_e64 s[46:47], 5, v66
	v_subbrev_co_u32_e32 v56, vcc, 0, v56, vcc
	v_sub_u32_e32 v57, 0, v56
	v_ldexp_f32 v13, v13, v57
	v_ldexp_f32 v15, v15, v57
	v_add_f32_e32 v57, -1.0, v13
	v_add_f32_e32 v70, 1.0, v13
	v_add_f32_e32 v67, 1.0, v57
	v_add_f32_e32 v71, -1.0, v70
	v_sub_f32_e32 v67, v13, v67
	v_sub_f32_e32 v13, v13, v71
	v_add_f32_e32 v13, v15, v13
	v_add_f32_e32 v67, v15, v67
	v_add_f32_e32 v15, v70, v13
	v_rcp_f32_e32 v71, v15
	v_add_f32_e32 v69, v57, v67
	v_sub_f32_e32 v57, v69, v57
	v_sub_f32_e32 v57, v67, v57
	v_sub_f32_e32 v67, v15, v70
	v_sub_f32_e32 v13, v13, v67
	v_mul_f32_e32 v67, v69, v71
	v_mul_f32_e32 v70, v15, v67
	v_fma_f32 v72, v67, v15, -v70
	v_fmac_f32_e32 v72, v67, v13
	v_add_f32_e32 v73, v70, v72
	v_sub_f32_e32 v74, v69, v73
	v_sub_f32_e32 v69, v69, v74
	v_sub_f32_e32 v70, v73, v70
	v_sub_f32_e32 v69, v69, v73
	v_add_f32_e32 v57, v57, v69
	v_sub_f32_e32 v69, v70, v72
	v_add_f32_e32 v57, v69, v57
	v_add_f32_e32 v69, v74, v57
	v_mul_f32_e32 v70, v71, v69
	v_mul_f32_e32 v72, v15, v70
	v_fma_f32 v15, v70, v15, -v72
	v_fmac_f32_e32 v15, v70, v13
	v_sub_f32_e32 v13, v74, v69
	v_add_f32_e32 v13, v57, v13
	v_add_f32_e32 v57, v72, v15
	v_sub_f32_e32 v73, v69, v57
	v_sub_f32_e32 v69, v69, v73
	v_sub_f32_e32 v72, v57, v72
	v_sub_f32_e32 v57, v69, v57
	v_add_f32_e32 v13, v13, v57
	v_sub_f32_e32 v15, v72, v15
	v_cvt_f32_i32_e32 v56, v56
	v_add_f32_e32 v13, v15, v13
; __device__ __forceinline__ void rglru_unit(const Params& p, const WS& ws, int j, int u, bool dry = false) {
;     ...
;   float ba[2][4], bx[2][4], sp[2][4];
; #pragma unroll
;   for (int mt = 0; mt < 2; ++mt)
; #pragma unroll
;     for (int jj = 0; jj < 4; ++jj) {
;       const int ch = j * 1024 + 128 * g + 32 * jq + 16 * mt + 4 * lq + jj;
;       ba[mt][jj] = p.ab_gate_a_b[ch]; bx[mt][jj] = p.ab_gate_x_b[ch];
;       sp[mt][jj] = 8.f * log1pf(__expf(-p.ab_lam[ch]));
;     }
;     ...
;   __syncthreads();
	v_add_f32_e32 v15, v67, v70
	v_add_f32_e32 v13, v73, v13
	v_sub_f32_e32 v57, v15, v67
	v_mul_f32_e32 v13, v71, v13
	v_sub_f32_e32 v57, v70, v57
	v_add_f32_e32 v13, v57, v13
	v_mul_f32_e32 v70, 0x3f317218, v56
	v_add_f32_e32 v57, v15, v13
	v_fma_f32 v71, v56, s10, -v70
	v_mul_f32_e32 v67, v57, v57
	v_fmac_f32_e32 v71, 0xb102e308, v56
	v_sub_f32_e32 v15, v57, v15
	v_fmamk_f32 v69, v67, 0x3e9b6dac, v192
	v_sub_f32_e32 v13, v13, v15
	v_add_f32_e32 v15, v70, v71
	v_fmaak_f32 v69, v67, v69, 0x3f2aaada
	v_sub_f32_e32 v56, v15, v70
	v_ldexp_f32 v70, v57, 1
	v_mul_f32_e32 v57, v57, v67
	v_mul_f32_e32 v57, v57, v69
	v_add_f32_e32 v67, v70, v57
	v_sub_f32_e32 v69, v67, v70
	v_ldexp_f32 v13, v13, 1
	v_sub_f32_e32 v57, v57, v69
	v_add_f32_e32 v13, v13, v57
	v_add_f32_e32 v57, v67, v13
	v_sub_f32_e32 v67, v57, v67
	v_sub_f32_e32 v13, v13, v67
	v_add_f32_e32 v67, v15, v57
	v_sub_f32_e32 v69, v67, v15
	v_sub_f32_e32 v70, v67, v69
	v_sub_f32_e32 v56, v71, v56
	v_sub_f32_e32 v15, v15, v70
	v_sub_f32_e32 v57, v57, v69
	v_add_f32_e32 v15, v57, v15
	v_add_f32_e32 v57, v56, v13
	v_sub_f32_e32 v69, v57, v56
	v_sub_f32_e32 v70, v57, v69
	v_sub_f32_e32 v56, v56, v70
	v_sub_f32_e32 v13, v13, v69
	v_add_f32_e32 v15, v57, v15
	v_add_f32_e32 v13, v13, v56
	v_add_f32_e32 v56, v67, v15
	v_sub_f32_e32 v57, v56, v67
	v_sub_f32_e32 v15, v15, v57
	v_add_f32_e32 v13, v13, v15
	v_add_f32_e32 v13, v56, v13
	v_cmp_neq_f32_e32 vcc, s21, v63
	v_mul_f32_e32 v15, 0xbfb8aa3b, v58
	v_exp_f32_e32 v15, v15
	v_cndmask_b32_e32 v13, v199, v13, vcc
	v_cmp_ngt_f32_e32 vcc, -1.0, v63
	v_cmp_lt_i32_e64 s[48:49], 6, v66
	v_cmp_eq_u32_e64 s[50:51], 7, v66
	v_cndmask_b32_e32 v13, v200, v13, vcc
	v_cmp_neq_f32_e32 vcc, -1.0, v63
	v_or_b32_e32 v108, 1, v84
	v_or_b32_e32 v104, 2, v84
	v_cndmask_b32_e32 v13, v194, v13, vcc
	v_cmp_lt_f32_e64 vcc, |v63|, s11
	v_or_b32_e32 v103, 3, v84
	v_or_b32_e32 v102, 4, v84
	v_cndmask_b32_e32 v13, v13, v63, vcc
	v_mul_f32_e32 v93, 0x41000000, v13
	v_add_f32_e32 v13, 1.0, v15
	v_add_f32_e32 v56, -1.0, v13
	v_sub_f32_e32 v57, v56, v13
	v_add_f32_e32 v57, 1.0, v57
	v_sub_f32_e32 v56, v15, v56
	v_add_f32_e32 v58, v56, v57
	v_frexp_mant_f32_e32 v63, v13
	v_cvt_f64_f32_e32 v[56:57], v13
	v_frexp_exp_i32_f64_e32 v56, v[56:57]
	v_cmp_gt_f32_e32 vcc, s3, v63
	v_or_b32_e32 v101, 5, v84
	v_or_b32_e32 v100, 6, v84
	v_subbrev_co_u32_e32 v56, vcc, 0, v56, vcc
	v_sub_u32_e32 v57, 0, v56
	v_ldexp_f32 v13, v13, v57
	v_ldexp_f32 v57, v58, v57
	v_add_f32_e32 v58, -1.0, v13
	v_add_f32_e32 v69, 1.0, v13
	v_add_f32_e32 v63, 1.0, v58
	v_add_f32_e32 v70, -1.0, v69
	v_sub_f32_e32 v63, v13, v63
	v_sub_f32_e32 v13, v13, v70
	v_add_f32_e32 v13, v57, v13
	v_add_f32_e32 v63, v57, v63
	v_add_f32_e32 v57, v69, v13
	v_rcp_f32_e32 v70, v57
	v_add_f32_e32 v67, v58, v63
	v_sub_f32_e32 v58, v67, v58
	v_sub_f32_e32 v58, v63, v58
	v_sub_f32_e32 v63, v57, v69
	v_sub_f32_e32 v13, v13, v63
	v_mul_f32_e32 v63, v67, v70
	v_mul_f32_e32 v69, v57, v63
	v_fma_f32 v71, v63, v57, -v69
	v_fmac_f32_e32 v71, v63, v13
	v_add_f32_e32 v72, v69, v71
	v_sub_f32_e32 v73, v67, v72
	v_sub_f32_e32 v67, v67, v73
	v_sub_f32_e32 v69, v72, v69
	v_sub_f32_e32 v67, v67, v72
	v_add_f32_e32 v58, v58, v67
	v_sub_f32_e32 v67, v69, v71
	v_add_f32_e32 v58, v67, v58
	v_add_f32_e32 v67, v73, v58
	v_mul_f32_e32 v69, v70, v67
	v_mul_f32_e32 v71, v57, v69
	v_fma_f32 v57, v69, v57, -v71
	v_fmac_f32_e32 v57, v69, v13
	v_sub_f32_e32 v13, v73, v67
	v_add_f32_e32 v13, v58, v13
	v_add_f32_e32 v58, v71, v57
	v_sub_f32_e32 v72, v67, v58
	v_sub_f32_e32 v67, v67, v72
	v_sub_f32_e32 v71, v58, v71
	v_sub_f32_e32 v58, v67, v58
	v_add_f32_e32 v13, v13, v58
	v_sub_f32_e32 v57, v71, v57
	v_cvt_f32_i32_e32 v56, v56
	v_add_f32_e32 v13, v57, v13
	v_add_f32_e32 v57, v63, v69
	v_add_f32_e32 v13, v72, v13
	v_sub_f32_e32 v58, v57, v63
	v_mul_f32_e32 v13, v70, v13
	v_sub_f32_e32 v58, v69, v58
	v_add_f32_e32 v13, v58, v13
	v_mul_f32_e32 v69, 0x3f317218, v56
	v_add_f32_e32 v58, v57, v13
	v_fma_f32 v70, v56, s10, -v69
	v_mul_f32_e32 v63, v58, v58
	v_fmac_f32_e32 v70, 0xb102e308, v56
	v_sub_f32_e32 v56, v58, v57
	v_fmamk_f32 v67, v63, 0x3e9b6dac, v192
	v_sub_f32_e32 v13, v13, v56
	v_add_f32_e32 v56, v69, v70
	v_fmaak_f32 v67, v63, v67, 0x3f2aaada
	v_sub_f32_e32 v57, v56, v69
	v_ldexp_f32 v69, v58, 1
	v_mul_f32_e32 v58, v58, v63
	v_mul_f32_e32 v58, v58, v67
	v_add_f32_e32 v63, v69, v58
	v_sub_f32_e32 v67, v63, v69
	v_ldexp_f32 v13, v13, 1
	v_sub_f32_e32 v58, v58, v67
	v_add_f32_e32 v13, v13, v58
	v_add_f32_e32 v58, v63, v13
	v_sub_f32_e32 v63, v58, v63
	v_sub_f32_e32 v13, v13, v63
	v_add_f32_e32 v63, v56, v58
	v_sub_f32_e32 v67, v63, v56
	v_sub_f32_e32 v69, v63, v67
	v_sub_f32_e32 v57, v70, v57
	v_sub_f32_e32 v56, v56, v69
	v_sub_f32_e32 v58, v58, v67
	v_add_f32_e32 v56, v58, v56
	v_add_f32_e32 v58, v57, v13
	v_sub_f32_e32 v67, v58, v57
	v_sub_f32_e32 v69, v58, v67
	v_sub_f32_e32 v57, v57, v69
	v_sub_f32_e32 v13, v13, v67
	v_add_f32_e32 v56, v58, v56
	v_add_f32_e32 v13, v13, v57
	v_add_f32_e32 v57, v63, v56
	v_sub_f32_e32 v58, v57, v63
	v_sub_f32_e32 v56, v56, v58
	v_add_f32_e32 v13, v13, v56
	v_add_f32_e32 v13, v57, v13
	v_cmp_neq_f32_e32 vcc, s21, v15
	v_mul_f32_e32 v56, 0xbfb8aa3b, v59
	v_exp_f32_e32 v58, v56
	v_cndmask_b32_e32 v13, v199, v13, vcc
	v_cmp_ngt_f32_e32 vcc, -1.0, v15
	v_add_u32_e32 v116, v81, v84
	v_add_u32_e32 v117, v80, v84
	v_cndmask_b32_e32 v13, v200, v13, vcc
	v_cmp_neq_f32_e32 vcc, -1.0, v15
	v_add_u32_e32 v118, v79, v84
	s_mov_b32 s12, 0
	v_cndmask_b32_e32 v13, v194, v13, vcc
	v_cmp_lt_f32_e64 vcc, |v15|, s11
	s_barrier
; __device__ __forceinline__ void rglru_unit(const Params& p, const WS& ws, int j, int u, bool dry = false) {
;     ...
;   float ba[2][4], bx[2][4], sp[2][4];
; #pragma unroll
;   for (int mt = 0; mt < 2; ++mt)
; #pragma unroll
;     for (int jj = 0; jj < 4; ++jj) {
;       const int ch = j * 1024 + 128 * g + 32 * jq + 16 * mt + 4 * lq + jj;
;       ba[mt][jj] = p.ab_gate_a_b[ch]; bx[mt][jj] = p.ab_gate_x_b[ch];
;       sp[mt][jj] = 8.f * log1pf(__expf(-p.ab_lam[ch]));
;     }
	s_nop 0
	v_cndmask_b32_e32 v13, v13, v15, vcc
	v_mul_f32_e32 v95, 0x41000000, v13
	v_add_f32_e32 v13, 1.0, v58
	v_add_f32_e32 v15, -1.0, v13
	v_sub_f32_e32 v56, v15, v13
	v_add_f32_e32 v56, 1.0, v56
	v_sub_f32_e32 v15, v58, v15
	v_add_f32_e32 v15, v15, v56
	v_frexp_mant_f32_e32 v59, v13
	v_cvt_f64_f32_e32 v[56:57], v13
	v_frexp_exp_i32_f64_e32 v56, v[56:57]
	v_cmp_gt_f32_e32 vcc, s3, v59
	s_nop 1
	v_subbrev_co_u32_e32 v56, vcc, 0, v56, vcc
	v_sub_u32_e32 v57, 0, v56
	v_ldexp_f32 v13, v13, v57
	v_ldexp_f32 v15, v15, v57
	v_add_f32_e32 v57, -1.0, v13
	v_add_f32_e32 v67, 1.0, v13
	v_add_f32_e32 v59, 1.0, v57
	v_add_f32_e32 v69, -1.0, v67
	v_sub_f32_e32 v59, v13, v59
	v_sub_f32_e32 v13, v13, v69
	v_add_f32_e32 v13, v15, v13
	v_add_f32_e32 v59, v15, v59
	v_add_f32_e32 v15, v67, v13
	v_rcp_f32_e32 v69, v15
	v_add_f32_e32 v63, v57, v59
	v_sub_f32_e32 v57, v63, v57
	v_sub_f32_e32 v57, v59, v57
	v_sub_f32_e32 v59, v15, v67
	v_sub_f32_e32 v13, v13, v59
	v_mul_f32_e32 v59, v63, v69
	v_mul_f32_e32 v67, v15, v59
	v_fma_f32 v70, v59, v15, -v67
	v_fmac_f32_e32 v70, v59, v13
	v_add_f32_e32 v71, v67, v70
	v_sub_f32_e32 v72, v63, v71
	v_sub_f32_e32 v63, v63, v72
	v_sub_f32_e32 v67, v71, v67
	v_sub_f32_e32 v63, v63, v71
	v_add_f32_e32 v57, v57, v63
	v_sub_f32_e32 v63, v67, v70
	v_add_f32_e32 v57, v63, v57
	v_add_f32_e32 v63, v72, v57
	v_mul_f32_e32 v67, v69, v63
	v_mul_f32_e32 v70, v15, v67
	v_fma_f32 v15, v67, v15, -v70
	v_fmac_f32_e32 v15, v67, v13
	v_sub_f32_e32 v13, v72, v63
	v_add_f32_e32 v13, v57, v13
	v_add_f32_e32 v57, v70, v15
	v_sub_f32_e32 v71, v63, v57
	v_sub_f32_e32 v63, v63, v71
	v_sub_f32_e32 v70, v57, v70
	v_sub_f32_e32 v57, v63, v57
	v_add_f32_e32 v13, v13, v57
	v_sub_f32_e32 v15, v70, v15
	v_cvt_f32_i32_e32 v56, v56
	v_add_f32_e32 v13, v15, v13
	v_add_f32_e32 v15, v59, v67
	v_add_f32_e32 v13, v71, v13
	v_sub_f32_e32 v57, v15, v59
	v_mul_f32_e32 v13, v69, v13
	v_sub_f32_e32 v57, v67, v57
	v_add_f32_e32 v13, v57, v13
	v_mul_f32_e32 v67, 0x3f317218, v56
	v_add_f32_e32 v57, v15, v13
	v_fma_f32 v69, v56, s10, -v67
	v_mul_f32_e32 v59, v57, v57
	v_fmac_f32_e32 v69, 0xb102e308, v56
	v_sub_f32_e32 v15, v57, v15
	v_fmamk_f32 v63, v59, 0x3e9b6dac, v192
	v_sub_f32_e32 v13, v13, v15
	v_add_f32_e32 v15, v67, v69
	v_fmaak_f32 v63, v59, v63, 0x3f2aaada
	v_sub_f32_e32 v56, v15, v67
	v_ldexp_f32 v67, v57, 1
	v_mul_f32_e32 v57, v57, v59
	v_mul_f32_e32 v57, v57, v63
	v_add_f32_e32 v59, v67, v57
	v_sub_f32_e32 v63, v59, v67
	v_ldexp_f32 v13, v13, 1
	v_sub_f32_e32 v57, v57, v63
	v_add_f32_e32 v13, v13, v57
	v_add_f32_e32 v57, v59, v13
	v_sub_f32_e32 v59, v57, v59
	v_sub_f32_e32 v13, v13, v59
	v_add_f32_e32 v59, v15, v57
	v_sub_f32_e32 v63, v59, v15
	v_sub_f32_e32 v67, v59, v63
	v_sub_f32_e32 v56, v69, v56
	v_sub_f32_e32 v15, v15, v67
	v_sub_f32_e32 v57, v57, v63
	v_add_f32_e32 v15, v57, v15
	v_add_f32_e32 v57, v56, v13
	v_sub_f32_e32 v63, v57, v56
	v_sub_f32_e32 v67, v57, v63
	v_sub_f32_e32 v56, v56, v67
	v_sub_f32_e32 v13, v13, v63
	v_add_f32_e32 v15, v57, v15
	v_add_f32_e32 v13, v13, v56
	v_add_f32_e32 v56, v59, v15
	v_sub_f32_e32 v57, v56, v59
	v_sub_f32_e32 v15, v15, v57
	v_add_f32_e32 v13, v13, v15
	v_add_f32_e32 v13, v56, v13
	v_cmp_neq_f32_e32 vcc, s21, v58
	s_waitcnt vmcnt(0)
	v_mul_f32_e32 v15, 0xbfb8aa3b, v52
	v_exp_f32_e32 v15, v15
	v_cndmask_b32_e32 v13, v199, v13, vcc
	v_cmp_ngt_f32_e32 vcc, -1.0, v58
	s_nop 1
	v_cndmask_b32_e32 v13, v200, v13, vcc
	v_cmp_neq_f32_e32 vcc, -1.0, v58
	s_nop 1
	v_cndmask_b32_e32 v13, v194, v13, vcc
	v_cmp_lt_f32_e64 vcc, |v58|, s11
	s_nop 1
	v_cndmask_b32_e32 v13, v13, v58, vcc
	v_mul_f32_e32 v96, 0x41000000, v13
	v_add_f32_e32 v13, 1.0, v15
	v_add_f32_e32 v52, -1.0, v13
	v_sub_f32_e32 v56, v52, v13
	v_add_f32_e32 v56, 1.0, v56
	v_sub_f32_e32 v52, v15, v52
	v_add_f32_e32 v52, v52, v56
	v_frexp_mant_f32_e32 v58, v13
	v_cvt_f64_f32_e32 v[56:57], v13
	v_frexp_exp_i32_f64_e32 v56, v[56:57]
	v_cmp_gt_f32_e32 vcc, s3, v58
	s_nop 1
	v_subbrev_co_u32_e32 v56, vcc, 0, v56, vcc
	v_sub_u32_e32 v57, 0, v56
	v_ldexp_f32 v13, v13, v57
	v_ldexp_f32 v52, v52, v57
	v_add_f32_e32 v57, -1.0, v13
	v_add_f32_e32 v63, 1.0, v13
	v_add_f32_e32 v58, 1.0, v57
	v_add_f32_e32 v67, -1.0, v63
	v_sub_f32_e32 v58, v13, v58
	v_sub_f32_e32 v13, v13, v67
	v_add_f32_e32 v13, v52, v13
	v_add_f32_e32 v58, v52, v58
	v_add_f32_e32 v52, v63, v13
	v_rcp_f32_e32 v67, v52
	v_add_f32_e32 v59, v57, v58
	v_sub_f32_e32 v57, v59, v57
	v_sub_f32_e32 v57, v58, v57
	v_sub_f32_e32 v58, v52, v63
	v_sub_f32_e32 v13, v13, v58
	v_mul_f32_e32 v58, v59, v67
	v_mul_f32_e32 v63, v52, v58
	v_fma_f32 v69, v58, v52, -v63
	v_fmac_f32_e32 v69, v58, v13
	v_add_f32_e32 v70, v63, v69
	v_sub_f32_e32 v71, v59, v70
	v_sub_f32_e32 v59, v59, v71
	v_sub_f32_e32 v63, v70, v63
	v_sub_f32_e32 v59, v59, v70
	v_add_f32_e32 v57, v57, v59
	v_sub_f32_e32 v59, v63, v69
	v_add_f32_e32 v57, v59, v57
	v_add_f32_e32 v59, v71, v57
	v_mul_f32_e32 v63, v67, v59
	v_mul_f32_e32 v69, v52, v63
	v_fma_f32 v52, v63, v52, -v69
	v_fmac_f32_e32 v52, v63, v13
	v_sub_f32_e32 v13, v71, v59
	v_add_f32_e32 v13, v57, v13
	v_add_f32_e32 v57, v69, v52
	v_sub_f32_e32 v70, v59, v57
	v_sub_f32_e32 v59, v59, v70
	v_sub_f32_e32 v69, v57, v69
	v_sub_f32_e32 v57, v59, v57
	v_add_f32_e32 v13, v13, v57
	v_sub_f32_e32 v52, v69, v52
	v_cvt_f32_i32_e32 v56, v56
	v_add_f32_e32 v13, v52, v13
	v_add_f32_e32 v52, v58, v63
	v_add_f32_e32 v13, v70, v13
	v_sub_f32_e32 v57, v52, v58
	v_mul_f32_e32 v13, v67, v13
	v_sub_f32_e32 v57, v63, v57
	v_add_f32_e32 v13, v57, v13
	v_mul_f32_e32 v63, 0x3f317218, v56
	v_add_f32_e32 v57, v52, v13
	v_fma_f32 v67, v56, s10, -v63
	v_mul_f32_e32 v58, v57, v57
	v_fmac_f32_e32 v67, 0xb102e308, v56
; __device__ __forceinline__ void rglru_unit(const Params& p, const WS& ws, int j, int u, bool dry = false) {
;     ...
;   float ba[2][4], bx[2][4], sp[2][4];
; #pragma unroll
;   for (int mt = 0; mt < 2; ++mt)
; #pragma unroll
;     for (int jj = 0; jj < 4; ++jj) {
;       const int ch = j * 1024 + 128 * g + 32 * jq + 16 * mt + 4 * lq + jj;
;       ba[mt][jj] = p.ab_gate_a_b[ch]; bx[mt][jj] = p.ab_gate_x_b[ch];
;       sp[mt][jj] = 8.f * log1pf(__expf(-p.ab_lam[ch]));
;     }
	v_sub_f32_e32 v52, v57, v52
	v_fmamk_f32 v59, v58, 0x3e9b6dac, v192
	v_sub_f32_e32 v13, v13, v52
	v_add_f32_e32 v52, v63, v67
	v_fmaak_f32 v59, v58, v59, 0x3f2aaada
	v_sub_f32_e32 v56, v52, v63
	v_ldexp_f32 v63, v57, 1
	v_mul_f32_e32 v57, v57, v58
	v_mul_f32_e32 v57, v57, v59
	v_add_f32_e32 v58, v63, v57
	v_sub_f32_e32 v59, v58, v63
	v_ldexp_f32 v13, v13, 1
	v_sub_f32_e32 v57, v57, v59
	v_add_f32_e32 v13, v13, v57
	v_add_f32_e32 v57, v58, v13
	v_sub_f32_e32 v58, v57, v58
	v_sub_f32_e32 v13, v13, v58
	v_add_f32_e32 v58, v52, v57
	v_sub_f32_e32 v59, v58, v52
	v_sub_f32_e32 v63, v58, v59
	v_sub_f32_e32 v56, v67, v56
	v_sub_f32_e32 v52, v52, v63
	v_sub_f32_e32 v57, v57, v59
	v_add_f32_e32 v52, v57, v52
	v_add_f32_e32 v57, v56, v13
	v_sub_f32_e32 v59, v57, v56
	v_sub_f32_e32 v63, v57, v59
	v_sub_f32_e32 v56, v56, v63
	v_sub_f32_e32 v13, v13, v59
	v_add_f32_e32 v52, v57, v52
	v_add_f32_e32 v13, v13, v56
	v_add_f32_e32 v56, v58, v52
	v_sub_f32_e32 v57, v56, v58
	v_sub_f32_e32 v52, v52, v57
	v_add_f32_e32 v13, v13, v52
	v_add_f32_e32 v13, v56, v13
	v_cmp_neq_f32_e32 vcc, s21, v15
	v_mul_f32_e32 v52, 0xbfb8aa3b, v53
	v_exp_f32_e32 v56, v52
	v_cndmask_b32_e32 v13, v199, v13, vcc
	v_cmp_ngt_f32_e32 vcc, -1.0, v15
	v_mov_b32_e32 v71, v12
	s_nop 0
	v_cndmask_b32_e32 v13, v200, v13, vcc
	v_cmp_neq_f32_e32 vcc, -1.0, v15
	s_nop 1
	v_cndmask_b32_e32 v13, v194, v13, vcc
	v_cmp_lt_f32_e64 vcc, |v15|, s11
	s_nop 1
	v_cndmask_b32_e32 v13, v13, v15, vcc
	v_mul_f32_e32 v97, 0x41000000, v13
	v_add_f32_e32 v13, 1.0, v56
	v_add_f32_e32 v15, -1.0, v13
	v_sub_f32_e32 v52, v15, v13
	v_add_f32_e32 v52, 1.0, v52
	v_sub_f32_e32 v15, v56, v15
	v_add_f32_e32 v15, v15, v52
	v_frexp_mant_f32_e32 v57, v13
	v_cvt_f64_f32_e32 v[52:53], v13
	v_frexp_exp_i32_f64_e32 v52, v[52:53]
	v_cmp_gt_f32_e32 vcc, s3, v57
	s_nop 1
	v_subbrev_co_u32_e32 v52, vcc, 0, v52, vcc
	v_sub_u32_e32 v53, 0, v52
	v_ldexp_f32 v13, v13, v53
	v_ldexp_f32 v15, v15, v53
	v_add_f32_e32 v53, -1.0, v13
	v_add_f32_e32 v59, 1.0, v13
	v_add_f32_e32 v57, 1.0, v53
	v_add_f32_e32 v63, -1.0, v59
	v_sub_f32_e32 v57, v13, v57
	v_sub_f32_e32 v13, v13, v63
	v_add_f32_e32 v13, v15, v13
	v_add_f32_e32 v57, v15, v57
	v_add_f32_e32 v15, v59, v13
	v_rcp_f32_e32 v63, v15
	v_add_f32_e32 v58, v53, v57
	v_sub_f32_e32 v53, v58, v53
	v_sub_f32_e32 v53, v57, v53
	v_sub_f32_e32 v57, v15, v59
	v_sub_f32_e32 v13, v13, v57
	v_mul_f32_e32 v57, v58, v63
	v_mul_f32_e32 v59, v15, v57
	v_fma_f32 v67, v57, v15, -v59
	v_fmac_f32_e32 v67, v57, v13
	v_add_f32_e32 v69, v59, v67
	v_sub_f32_e32 v70, v58, v69
	v_sub_f32_e32 v58, v58, v70
	v_sub_f32_e32 v59, v69, v59
	v_sub_f32_e32 v58, v58, v69
	v_add_f32_e32 v53, v53, v58
	v_sub_f32_e32 v58, v59, v67
	v_add_f32_e32 v53, v58, v53
	v_add_f32_e32 v58, v70, v53
	v_mul_f32_e32 v59, v63, v58
	v_mul_f32_e32 v67, v15, v59
	v_fma_f32 v15, v59, v15, -v67
	v_fmac_f32_e32 v15, v59, v13
	v_sub_f32_e32 v13, v70, v58
	v_add_f32_e32 v13, v53, v13
	v_add_f32_e32 v53, v67, v15
	v_sub_f32_e32 v69, v58, v53
	v_sub_f32_e32 v58, v58, v69
	v_sub_f32_e32 v67, v53, v67
	v_sub_f32_e32 v53, v58, v53
	v_add_f32_e32 v13, v13, v53
	v_sub_f32_e32 v15, v67, v15
	v_cvt_f32_i32_e32 v52, v52
	v_add_f32_e32 v13, v15, v13
	v_add_f32_e32 v15, v57, v59
	v_add_f32_e32 v13, v69, v13
	v_sub_f32_e32 v53, v15, v57
	v_mul_f32_e32 v13, v63, v13
	v_sub_f32_e32 v53, v59, v53
	v_add_f32_e32 v13, v53, v13
	v_mul_f32_e32 v59, 0x3f317218, v52
	v_add_f32_e32 v53, v15, v13
	v_fma_f32 v63, v52, s10, -v59
	v_mul_f32_e32 v57, v53, v53
	v_fmac_f32_e32 v63, 0xb102e308, v52
	v_sub_f32_e32 v15, v53, v15
	v_fmamk_f32 v58, v57, 0x3e9b6dac, v192
	v_sub_f32_e32 v13, v13, v15
	v_add_f32_e32 v15, v59, v63
	v_fmaak_f32 v58, v57, v58, 0x3f2aaada
	v_sub_f32_e32 v52, v15, v59
	v_ldexp_f32 v59, v53, 1
	v_mul_f32_e32 v53, v53, v57
	v_mul_f32_e32 v53, v53, v58
	v_add_f32_e32 v57, v59, v53
	v_sub_f32_e32 v58, v57, v59
	v_ldexp_f32 v13, v13, 1
	v_sub_f32_e32 v53, v53, v58
	v_add_f32_e32 v13, v13, v53
	v_add_f32_e32 v53, v57, v13
	v_sub_f32_e32 v57, v53, v57
	v_sub_f32_e32 v13, v13, v57
	v_add_f32_e32 v57, v15, v53
	v_sub_f32_e32 v58, v57, v15
	v_sub_f32_e32 v59, v57, v58
	v_sub_f32_e32 v52, v63, v52
	v_sub_f32_e32 v15, v15, v59
	v_sub_f32_e32 v53, v53, v58
	v_add_f32_e32 v15, v53, v15
	v_add_f32_e32 v53, v52, v13
	v_sub_f32_e32 v58, v53, v52
	v_sub_f32_e32 v59, v53, v58
	v_sub_f32_e32 v52, v52, v59
	v_sub_f32_e32 v13, v13, v58
	v_add_f32_e32 v15, v53, v15
	v_add_f32_e32 v13, v13, v52
	v_add_f32_e32 v52, v57, v15
	v_sub_f32_e32 v53, v52, v57
	v_sub_f32_e32 v15, v15, v53
	v_add_f32_e32 v13, v13, v15
	v_add_f32_e32 v13, v52, v13
	v_cmp_neq_f32_e32 vcc, s21, v56
	v_mul_f32_e32 v15, 0xbfb8aa3b, v54
	v_exp_f32_e32 v15, v15
	v_cndmask_b32_e32 v13, v199, v13, vcc
	v_cmp_ngt_f32_e32 vcc, -1.0, v56
	v_lshlrev_b32_e32 v70, 1, v14
	s_nop 0
	v_cndmask_b32_e32 v13, v200, v13, vcc
	v_cmp_neq_f32_e32 vcc, -1.0, v56
	s_nop 1
	v_cndmask_b32_e32 v13, v194, v13, vcc
	v_cmp_lt_f32_e64 vcc, |v56|, s11
	s_nop 1
	v_cndmask_b32_e32 v13, v13, v56, vcc
	v_mul_f32_e32 v98, 0x41000000, v13
	v_add_f32_e32 v13, 1.0, v15
	v_add_f32_e32 v52, -1.0, v13
	v_sub_f32_e32 v53, v52, v13
	v_add_f32_e32 v53, 1.0, v53
	v_sub_f32_e32 v52, v15, v52
	v_add_f32_e32 v54, v52, v53
	v_frexp_mant_f32_e32 v56, v13
	v_cvt_f64_f32_e32 v[52:53], v13
	v_frexp_exp_i32_f64_e32 v52, v[52:53]
	v_cmp_gt_f32_e32 vcc, s3, v56
	s_nop 1
	v_subbrev_co_u32_e32 v52, vcc, 0, v52, vcc
	v_sub_u32_e32 v53, 0, v52
	v_ldexp_f32 v13, v13, v53
	v_ldexp_f32 v53, v54, v53
	v_add_f32_e32 v54, -1.0, v13
	v_add_f32_e32 v58, 1.0, v13
	v_add_f32_e32 v56, 1.0, v54
	v_add_f32_e32 v59, -1.0, v58
	v_sub_f32_e32 v56, v13, v56
	v_sub_f32_e32 v13, v13, v59
; __device__ __forceinline__ void rglru_unit(const Params& p, const WS& ws, int j, int u, bool dry = false) {
;     ...
;   float ba[2][4], bx[2][4], sp[2][4];
; #pragma unroll
;   for (int mt = 0; mt < 2; ++mt)
; #pragma unroll
;     for (int jj = 0; jj < 4; ++jj) {
;       const int ch = j * 1024 + 128 * g + 32 * jq + 16 * mt + 4 * lq + jj;
;       ba[mt][jj] = p.ab_gate_a_b[ch]; bx[mt][jj] = p.ab_gate_x_b[ch];
;       sp[mt][jj] = 8.f * log1pf(__expf(-p.ab_lam[ch]));
;     }
	v_add_f32_e32 v13, v53, v13
	v_add_f32_e32 v56, v53, v56
	v_add_f32_e32 v53, v58, v13
	v_rcp_f32_e32 v59, v53
	v_add_f32_e32 v57, v54, v56
	v_sub_f32_e32 v54, v57, v54
	v_sub_f32_e32 v54, v56, v54
	v_sub_f32_e32 v56, v53, v58
	v_sub_f32_e32 v13, v13, v56
	v_mul_f32_e32 v56, v57, v59
	v_mul_f32_e32 v58, v53, v56
	v_fma_f32 v63, v56, v53, -v58
	v_fmac_f32_e32 v63, v56, v13
	v_add_f32_e32 v67, v58, v63
	v_sub_f32_e32 v69, v57, v67
	v_sub_f32_e32 v57, v57, v69
	v_sub_f32_e32 v58, v67, v58
	v_sub_f32_e32 v57, v57, v67
	v_add_f32_e32 v54, v54, v57
	v_sub_f32_e32 v57, v58, v63
	v_add_f32_e32 v54, v57, v54
	v_add_f32_e32 v57, v69, v54
	v_mul_f32_e32 v58, v59, v57
	v_mul_f32_e32 v63, v53, v58
	v_fma_f32 v53, v58, v53, -v63
	v_fmac_f32_e32 v53, v58, v13
	v_sub_f32_e32 v13, v69, v57
	v_add_f32_e32 v13, v54, v13
	v_add_f32_e32 v54, v63, v53
	v_sub_f32_e32 v67, v57, v54
	v_sub_f32_e32 v57, v57, v67
	v_sub_f32_e32 v63, v54, v63
	v_sub_f32_e32 v54, v57, v54
	v_add_f32_e32 v13, v13, v54
	v_sub_f32_e32 v53, v63, v53
	v_cvt_f32_i32_e32 v52, v52
	v_add_f32_e32 v13, v53, v13
	v_add_f32_e32 v53, v56, v58
	v_add_f32_e32 v13, v67, v13
	v_sub_f32_e32 v54, v53, v56
	v_mul_f32_e32 v13, v59, v13
	v_sub_f32_e32 v54, v58, v54
	v_add_f32_e32 v13, v54, v13
	v_mul_f32_e32 v58, 0x3f317218, v52
	v_add_f32_e32 v54, v53, v13
	v_fma_f32 v59, v52, s10, -v58
	v_mul_f32_e32 v56, v54, v54
	v_fmac_f32_e32 v59, 0xb102e308, v52
	v_sub_f32_e32 v52, v54, v53
	v_fmamk_f32 v57, v56, 0x3e9b6dac, v192
	v_sub_f32_e32 v13, v13, v52
	v_add_f32_e32 v52, v58, v59
	v_fmaak_f32 v57, v56, v57, 0x3f2aaada
	v_sub_f32_e32 v53, v52, v58
	v_ldexp_f32 v58, v54, 1
	v_mul_f32_e32 v54, v54, v56
	v_mul_f32_e32 v54, v54, v57
	v_add_f32_e32 v56, v58, v54
	v_sub_f32_e32 v57, v56, v58
	v_ldexp_f32 v13, v13, 1
	v_sub_f32_e32 v54, v54, v57
	v_add_f32_e32 v13, v13, v54
	v_add_f32_e32 v54, v56, v13
	v_sub_f32_e32 v56, v54, v56
	v_sub_f32_e32 v13, v13, v56
	v_add_f32_e32 v56, v52, v54
	v_sub_f32_e32 v57, v56, v52
	v_sub_f32_e32 v58, v56, v57
	v_sub_f32_e32 v53, v59, v53
	v_sub_f32_e32 v52, v52, v58
	v_sub_f32_e32 v54, v54, v57
	v_add_f32_e32 v52, v54, v52
	v_add_f32_e32 v54, v53, v13
	v_sub_f32_e32 v57, v54, v53
	v_sub_f32_e32 v58, v54, v57
	v_sub_f32_e32 v53, v53, v58
	v_sub_f32_e32 v13, v13, v57
	v_add_f32_e32 v52, v54, v52
	v_add_f32_e32 v13, v13, v53
	v_add_f32_e32 v53, v56, v52
	v_sub_f32_e32 v54, v53, v56
	v_sub_f32_e32 v52, v52, v54
	v_add_f32_e32 v13, v13, v52
	v_add_f32_e32 v13, v53, v13
	v_cmp_neq_f32_e32 vcc, s21, v15
	v_mul_f32_e32 v52, 0xbfb8aa3b, v55
	v_exp_f32_e32 v54, v52
	v_cndmask_b32_e32 v13, v199, v13, vcc
	v_cmp_ngt_f32_e32 vcc, -1.0, v15
	v_mov_b32_e32 v69, v12
	s_nop 0
	v_cndmask_b32_e32 v13, v200, v13, vcc
	v_cmp_neq_f32_e32 vcc, -1.0, v15
	s_nop 1
	v_cndmask_b32_e32 v13, v194, v13, vcc
	v_cmp_lt_f32_e64 vcc, |v15|, s11
	s_nop 1
	v_cndmask_b32_e32 v13, v13, v15, vcc
	v_mul_f32_e32 v99, 0x41000000, v13
	v_add_f32_e32 v13, 1.0, v54
	v_add_f32_e32 v15, -1.0, v13
	v_sub_f32_e32 v52, v15, v13
	v_add_f32_e32 v52, 1.0, v52
	v_sub_f32_e32 v15, v54, v15
	v_add_f32_e32 v15, v15, v52
	v_frexp_mant_f32_e32 v55, v13
	v_cvt_f64_f32_e32 v[52:53], v13
	v_frexp_exp_i32_f64_e32 v52, v[52:53]
	v_cmp_gt_f32_e32 vcc, s3, v55
	s_nop 1
	v_subbrev_co_u32_e32 v52, vcc, 0, v52, vcc
	v_sub_u32_e32 v53, 0, v52
	v_ldexp_f32 v13, v13, v53
	v_ldexp_f32 v15, v15, v53
	v_add_f32_e32 v53, -1.0, v13
	v_add_f32_e32 v57, 1.0, v13
	v_add_f32_e32 v55, 1.0, v53
	v_add_f32_e32 v58, -1.0, v57
	v_sub_f32_e32 v55, v13, v55
	v_sub_f32_e32 v13, v13, v58
	v_add_f32_e32 v13, v15, v13
	v_add_f32_e32 v55, v15, v55
	v_add_f32_e32 v15, v57, v13
	v_rcp_f32_e32 v58, v15
	v_add_f32_e32 v56, v53, v55
	v_sub_f32_e32 v53, v56, v53
	v_sub_f32_e32 v53, v55, v53
	v_sub_f32_e32 v55, v15, v57
	v_sub_f32_e32 v13, v13, v55
	v_mul_f32_e32 v55, v56, v58
	v_mul_f32_e32 v57, v15, v55
	v_fma_f32 v59, v55, v15, -v57
	v_fmac_f32_e32 v59, v55, v13
	v_add_f32_e32 v63, v57, v59
	v_sub_f32_e32 v67, v56, v63
	v_sub_f32_e32 v56, v56, v67
	v_sub_f32_e32 v57, v63, v57
	v_sub_f32_e32 v56, v56, v63
	v_add_f32_e32 v53, v53, v56
	v_sub_f32_e32 v56, v57, v59
	v_add_f32_e32 v53, v56, v53
	v_add_f32_e32 v56, v67, v53
	v_mul_f32_e32 v57, v58, v56
	v_mul_f32_e32 v59, v15, v57
	v_fma_f32 v15, v57, v15, -v59
	v_fmac_f32_e32 v15, v57, v13
	v_sub_f32_e32 v13, v67, v56
	v_add_f32_e32 v13, v53, v13
	v_add_f32_e32 v53, v59, v15
	v_sub_f32_e32 v63, v56, v53
	v_sub_f32_e32 v56, v56, v63
	v_sub_f32_e32 v59, v53, v59
	v_sub_f32_e32 v53, v56, v53
	v_add_f32_e32 v13, v13, v53
	v_sub_f32_e32 v15, v59, v15
	v_cvt_f32_i32_e32 v52, v52
	v_add_f32_e32 v13, v15, v13
	v_add_f32_e32 v15, v55, v57
	v_add_f32_e32 v13, v63, v13
	v_sub_f32_e32 v53, v15, v55
	v_mul_f32_e32 v13, v58, v13
	v_sub_f32_e32 v53, v57, v53
	v_add_f32_e32 v13, v53, v13
	v_mul_f32_e32 v57, 0x3f317218, v52
	v_add_f32_e32 v53, v15, v13
	v_fma_f32 v58, v52, s10, -v57
; __device__ __forceinline__ float bf2f(bf16_t v) { return __uint_as_float(((unsigned)v) << 16); }
; __device__ __forceinline__ void rglru_unit(const Params& p, const WS& ws, int j, int u, bool dry = false) {
;     ...
;   float ba[2][4], bx[2][4], sp[2][4];
; #pragma unroll
;   for (int mt = 0; mt < 2; ++mt)
; #pragma unroll
;     for (int jj = 0; jj < 4; ++jj) {
;       const int ch = j * 1024 + 128 * g + 32 * jq + 16 * mt + 4 * lq + jj;
;       ba[mt][jj] = p.ab_gate_a_b[ch]; bx[mt][jj] = p.ab_gate_x_b[ch];
;       sp[mt][jj] = 8.f * log1pf(__expf(-p.ab_lam[ch]));
;     }
;     ...
;   bf16_t ypend[8];
;   int ypend_t0 = -1;
;   auto flush_y = [&]() {
;     if (ypend_t0 >= 0) {
; #pragma unroll
;       for (int i = 0; i < 8; ++i) {
;         const int t = ypend_t0 + 8 * ssg + i;
;         if (t < T_ && !dry) ws.GA[(size_t)(b * T_ + t) * 1024 + 128 * g + 32 * jq + sc] = ypend[i];
;       }
;     }
;   };
;   auto body = [&](int tile, u32x4 (&xin)[4], bf16_t (&gav)[8]) {
;     const int t0 = 64 * tile;
; #pragma unroll
;     for (int i = 0; i < 4; ++i) {
;       const int ci = tid + 256 * i; const int row = ci >> 4, ch = ci & 15;
;       *(u32x4*)(XC + row * 136 + 8 * ch) = xin[i];
;     }
;     float gcur[8];
; #pragma unroll
;     for (int i = 0; i < 8; ++i) gcur[i] = bf2f(gav[i]);
;     __syncthreads();
;     flush_y();
	v_mul_f32_e32 v55, v53, v53
	v_fmac_f32_e32 v58, 0xb102e308, v52
	v_sub_f32_e32 v15, v53, v15
	v_fmamk_f32 v56, v55, 0x3e9b6dac, v192
	v_sub_f32_e32 v13, v13, v15
	v_add_f32_e32 v15, v57, v58
	v_fmaak_f32 v56, v55, v56, 0x3f2aaada
	v_sub_f32_e32 v52, v15, v57
	v_ldexp_f32 v57, v53, 1
	v_mul_f32_e32 v53, v53, v55
	v_mul_f32_e32 v53, v53, v56
	v_add_f32_e32 v55, v57, v53
	v_sub_f32_e32 v56, v55, v57
	v_ldexp_f32 v13, v13, 1
	v_sub_f32_e32 v53, v53, v56
	v_add_f32_e32 v13, v13, v53
	v_add_f32_e32 v53, v55, v13
	v_sub_f32_e32 v55, v53, v55
	v_sub_f32_e32 v13, v13, v55
	v_add_f32_e32 v55, v15, v53
	v_sub_f32_e32 v56, v55, v15
	v_sub_f32_e32 v57, v55, v56
	v_sub_f32_e32 v52, v58, v52
	v_sub_f32_e32 v15, v15, v57
	v_sub_f32_e32 v53, v53, v56
	v_add_f32_e32 v15, v53, v15
	v_add_f32_e32 v53, v52, v13
	v_sub_f32_e32 v56, v53, v52
	v_sub_f32_e32 v57, v53, v56
	v_sub_f32_e32 v52, v52, v57
	v_sub_f32_e32 v13, v13, v56
	v_add_f32_e32 v15, v53, v15
	v_add_f32_e32 v13, v13, v52
	v_add_f32_e32 v52, v55, v15
	v_sub_f32_e32 v53, v52, v55
	v_sub_f32_e32 v15, v15, v53
	v_add_f32_e32 v13, v13, v15
	v_mul_lo_u32 v15, v79, s19
	v_add3_u32 v106, s8, v15, v62
	v_mul_lo_u32 v15, v80, s19
	v_add3_u32 v107, s8, v15, v62
	v_mul_lo_u32 v15, v81, s19
	v_add_f32_e32 v13, v52, v13
	v_cmp_neq_f32_e32 vcc, s21, v54
	v_add3_u32 v109, s8, v15, v62
	v_mul_lo_u32 v15, v82, s19
	v_cndmask_b32_e32 v13, v199, v13, vcc
	v_cmp_ngt_f32_e32 vcc, -1.0, v54
	v_add3_u32 v110, s8, v15, v62
	v_ashrrev_i32_e32 v15, 2, v61
	v_cndmask_b32_e32 v13, v200, v13, vcc
	v_cmp_neq_f32_e32 vcc, -1.0, v54
	v_bfi_b32 v15, -16, v15, v61
	v_mul_lo_u32 v52, v15, s19
	v_cndmask_b32_e32 v13, v194, v13, vcc
	v_cmp_lt_f32_e64 vcc, |v54|, s11
	v_add_u32_e32 v53, s8, v52
	v_lshlrev_b32_e32 v52, 4, v64
	v_cndmask_b32_e32 v13, v13, v54, vcc
	v_mul_f32_e32 v105, 0x41000000, v13
	v_and_b32_e32 v13, 15, v61
	v_add_u32_e32 v111, v53, v52
	v_add_u32_e32 v52, s8, v52
	v_mul_u32_u24_e32 v13, 0x88, v13
	v_mad_u64_u32 v[72:73], s[10:11], v15, s9, v[52:53]
	v_lshl_add_u64 v[14:15], s[54:55], 0, v[70:71]
	v_lshl_add_u32 v112, v13, 1, v52
	v_lshlrev_b32_e32 v13, 1, v65
	s_movk_i32 s9, 0x108
	v_lshl_add_u64 v[14:15], v[14:15], 0, s[92:93]
	v_add3_u32 v113, v53, s92, v13
	v_mad_u64_u32 v[52:53], s[10:11], v66, s9, v[60:61]
	v_lshl_add_u64 v[74:75], v[14:15], 0, v[68:69]
	v_lshl_add_u64 v[14:15], s[4:5], 0, v[70:71]
	v_mov_b32_e32 v63, v12
	v_lshl_add_u32 v114, v52, 2, s8
	v_cmp_lt_i32_e32 vcc, 0, v66
	v_or_b32_e32 v73, 7, v84
	v_lshl_add_u64 v[76:77], v[14:15], 0, v[62:63]
	v_add_u32_e32 v69, v84, v83
	v_add_u32_e32 v71, v82, v84
	s_mov_b32 s4, -1
	s_mov_b32 s101, 0
.LBB0_1376:
	s_cmp_lt_i32 s4, 0
	ds_write_b128 v106, v[20:23]
	ds_write_b128 v107, v[24:27]
	ds_write_b128 v109, v[28:31]
	ds_write_b128 v110, v[32:35]
	s_waitcnt lgkmcnt(0)
	s_barrier
	s_cbranch_scc1 .LBB0_1394
	s_cmpk_gt_i32 s4, 0x7d0
	s_cbranch_scc1 .Lrg_fslow1
	v_add_u32_e32 v13, s4, v83
	v_add_u32_e32 v52, v13, v84
	v_ashrrev_i32_e32 v53, 31, v52
	v_lshlrev_b64 v[52:53], 11, v[52:53]
	v_lshl_add_u64 v[52:53], v[74:75], 0, v[52:53]
	global_store_short v[52:53], v58, off
	v_add_u32_e32 v52, v13, v104
	v_ashrrev_i32_e32 v53, 31, v52
	v_lshlrev_b64 v[52:53], 11, v[52:53]
	v_lshl_add_u64 v[52:53], v[74:75], 0, v[52:53]
	global_store_short v[52:53], v56, off
	v_add_u32_e32 v52, v13, v102
	v_ashrrev_i32_e32 v53, 31, v52
	v_lshlrev_b64 v[52:53], 11, v[52:53]
	v_lshl_add_u64 v[52:53], v[74:75], 0, v[52:53]
	global_store_short v[52:53], v54, off
	v_add_u32_e32 v52, v13, v100
	v_ashrrev_i32_e32 v53, 31, v52
	v_lshlrev_b64 v[52:53], 11, v[52:53]
	v_lshl_add_u64 v[52:53], v[74:75], 0, v[52:53]
	global_store_short v[52:53], v14, off
	v_add_u32_e32 v52, v13, v108
	v_ashrrev_i32_e32 v53, 31, v52
	v_lshlrev_b64 v[52:53], 11, v[52:53]
	v_lshl_add_u64 v[52:53], v[74:75], 0, v[52:53]
	global_store_short v[52:53], v59, off
	v_add_u32_e32 v52, v13, v103
	v_ashrrev_i32_e32 v53, 31, v52
	v_lshlrev_b64 v[52:53], 11, v[52:53]
	v_lshl_add_u64 v[52:53], v[74:75], 0, v[52:53]
	global_store_short v[52:53], v57, off
	v_add_u32_e32 v52, v13, v101
	v_ashrrev_i32_e32 v53, 31, v52
	v_lshlrev_b64 v[52:53], 11, v[52:53]
	v_lshl_add_u64 v[52:53], v[74:75], 0, v[52:53]
	global_store_short v[52:53], v55, off
	v_add_u32_e32 v52, v13, v73
	v_ashrrev_i32_e32 v53, 31, v52
	v_lshlrev_b64 v[52:53], 11, v[52:53]
	v_lshl_add_u64 v[52:53], v[74:75], 0, v[52:53]
	global_store_short v[52:53], v15, off
	s_branch .LBB0_1394
.Lrg_fslow1:
	v_add_u32_e32 v13, s4, v83
	v_cmp_gt_i32_e64 s[52:53], s15, v13
	s_and_saveexec_b64 s[4:5], s[52:53]
	s_cbranch_execz .LBB0_1385
	v_add_u32_e32 v52, v13, v84
	v_ashrrev_i32_e32 v53, 31, v52
	v_lshlrev_b64 v[52:53], 11, v[52:53]
	v_lshl_add_u64 v[52:53], v[74:75], 0, v[52:53]
	global_store_short v[52:53], v58, off
	s_or_b64 exec, exec, s[4:5]
	v_cmp_gt_i32_e64 s[52:53], s16, v13
	s_and_saveexec_b64 s[4:5], s[52:53]
	s_cbranch_execnz .LBB0_1386

; __device__ __forceinline__ void rglru_unit(const Params& p, const WS& ws, int j, int u, bool dry = false) {
;     ...
;   auto prefetch = [&](int tile, u32x4 (&xin)[4], bf16_t (&gav)[8]) {
;     const int t0 = 64 * tile;
; #pragma unroll
;     for (int i = 0; i < 4; ++i) {
;       const int ci = tid + 256 * i; const int row = ci >> 4, ch = ci & 15; const int t = t0 + row;
;       xin[i] = (u32x4){0, 0, 0, 0};
;       if (t < T_) xin[i] = *(const u32x4*)(ws.XA + (size_t)(b * T_ + t) * 1024 + 128 * g + 8 * ch);
;     }
; #pragma unroll
;     for (int i = 0; i < 8; ++i) {
;       const int t = t0 + 8 * ssg + i;
;       gav[i] = 0;
;       if (t < T_) gav[i] = ws.GA[(size_t)(b * T_ + t) * 1024 + 128 * g + 32 * jq + sc];
;     }
;   };
.LBB0_1394:
	s_add_i32 s13, s7, -1
	s_cmp_gt_u32 s13, 30
	v_mov_b32_e32 v133, v127
	v_mov_b32_e32 v134, v128
	v_mov_b32_e32 v131, v123
	v_mov_b32_e32 v132, v124
	v_mov_b32_e32 v129, v121
	v_mov_b32_e32 v130, v122
	v_mov_b32_e32 v125, v119
	v_mov_b32_e32 v126, v120
	s_cbranch_scc1 .LBB0_1420
	s_cmpk_gt_i32 s6, 0x750
	s_cbranch_scc1 .Lrg_pslow1
	v_add_u32_e32 v14, s6, v118
	v_add_u32_e32 v14, 0x80, v14
	v_ashrrev_i32_e32 v15, 31, v14
	v_lshlrev_b64 v[14:15], 11, v[14:15]
	v_lshl_add_u64 v[14:15], v[76:77], 0, v[14:15]
	global_load_dwordx4 v[20:23], v[14:15], off
	v_add_u32_e32 v14, s6, v117
	v_add_u32_e32 v14, 0x80, v14
	v_ashrrev_i32_e32 v15, 31, v14
	v_lshlrev_b64 v[14:15], 11, v[14:15]
	v_lshl_add_u64 v[14:15], v[76:77], 0, v[14:15]
	global_load_dwordx4 v[24:27], v[14:15], off
	v_add_u32_e32 v14, s6, v116
	v_add_u32_e32 v14, 0x80, v14
	v_ashrrev_i32_e32 v15, 31, v14
	v_lshlrev_b64 v[14:15], 11, v[14:15]
	v_lshl_add_u64 v[14:15], v[76:77], 0, v[14:15]
	global_load_dwordx4 v[28:31], v[14:15], off
	v_add_u32_e32 v14, s6, v71
	v_add_u32_e32 v14, 0x80, v14
	v_ashrrev_i32_e32 v15, 31, v14
	v_lshlrev_b64 v[14:15], 11, v[14:15]
	v_lshl_add_u64 v[14:15], v[76:77], 0, v[14:15]
	global_load_dwordx4 v[32:35], v[14:15], off
	v_add_u32_e32 v14, s6, v69
	v_add_u32_e32 v14, 0x80, v14
	v_ashrrev_i32_e32 v15, 31, v14
	v_lshlrev_b64 v[14:15], 11, v[14:15]
	v_lshl_add_u64 v[14:15], v[74:75], 0, v[14:15]
	global_load_ushort v126, v[14:15], off
	v_add_u32_e32 v14, s6, v69
	v_add_u32_e32 v14, 0x81, v14
	v_ashrrev_i32_e32 v15, 31, v14
	v_lshlrev_b64 v[14:15], 11, v[14:15]
	v_lshl_add_u64 v[14:15], v[74:75], 0, v[14:15]
	global_load_ushort v125, v[14:15], off
	v_add_u32_e32 v14, s6, v69
	v_add_u32_e32 v14, 0x82, v14
	v_ashrrev_i32_e32 v15, 31, v14
	v_lshlrev_b64 v[14:15], 11, v[14:15]
	v_lshl_add_u64 v[14:15], v[74:75], 0, v[14:15]
	global_load_ushort v130, v[14:15], off
	v_add_u32_e32 v14, s6, v69
	v_add_u32_e32 v14, 0x83, v14
	v_ashrrev_i32_e32 v15, 31, v14
	v_lshlrev_b64 v[14:15], 11, v[14:15]
	v_lshl_add_u64 v[14:15], v[74:75], 0, v[14:15]
	global_load_ushort v129, v[14:15], off
	v_add_u32_e32 v14, s6, v69
	v_add_u32_e32 v14, 0x84, v14
	v_ashrrev_i32_e32 v15, 31, v14
	v_lshlrev_b64 v[14:15], 11, v[14:15]
	v_lshl_add_u64 v[14:15], v[74:75], 0, v[14:15]
	global_load_ushort v132, v[14:15], off
	v_add_u32_e32 v14, s6, v69
	v_add_u32_e32 v14, 0x85, v14
	v_ashrrev_i32_e32 v15, 31, v14
	v_lshlrev_b64 v[14:15], 11, v[14:15]
	v_lshl_add_u64 v[14:15], v[74:75], 0, v[14:15]
	global_load_ushort v131, v[14:15], off
	v_add_u32_e32 v14, s6, v69
	v_add_u32_e32 v14, 0x86, v14
	v_ashrrev_i32_e32 v15, 31, v14
	v_lshlrev_b64 v[14:15], 11, v[14:15]
	v_lshl_add_u64 v[14:15], v[74:75], 0, v[14:15]
	global_load_ushort v134, v[14:15], off
	v_add_u32_e32 v14, s6, v69
	v_add_u32_e32 v14, 0x87, v14
	v_ashrrev_i32_e32 v15, 31, v14
	v_lshlrev_b64 v[14:15], 11, v[14:15]
	v_lshl_add_u64 v[14:15], v[74:75], 0, v[14:15]
	global_load_ushort v133, v[14:15], off
	s_branch .LBB0_1420
.Lrg_pslow1:
	v_add_u32_e32 v13, s6, v79
	v_mov_b32_e32 v24, v12
	v_mov_b32_e32 v25, v12
	v_add_u32_e32 v13, 0x80, v13
	v_mov_b32_e32 v26, v12
	v_mov_b32_e32 v27, v12
	v_mov_b64_e32 v[20:21], v[24:25]
	v_cmp_gt_i32_e64 s[52:53], s15, v13
	v_mov_b64_e32 v[22:23], v[26:27]
	s_and_saveexec_b64 s[4:5], s[52:53]
	s_cbranch_execz .LBB0_1397
	v_add_u32_e32 v13, s6, v118
	v_add_u32_e32 v14, 0x80, v13
	v_ashrrev_i32_e32 v15, 31, v14
	v_lshlrev_b64 v[14:15], 11, v[14:15]
	v_lshl_add_u64 v[14:15], v[76:77], 0, v[14:15]
	global_load_dwordx4 v[20:23], v[14:15], off

; __device__ __forceinline__ float bf2f(bf16_t v) { return __uint_as_float(((unsigned)v) << 16); }
; __device__ __forceinline__ bf16_t f2bf(float f) { return (bf16_t)(cvt_pk_bf16(f, 0.f) & 0xffffu); }
; __device__ __forceinline__ float siluf_(float x) { return x * __builtin_amdgcn_rcpf(1.f + __expf(-x)); }
; __device__ __forceinline__ void rglru_unit(const Params& p, const WS& ws, int j, int u, bool dry = false) {
;     ...
;   auto body = [&](int tile, u32x4 (&xin)[4], bf16_t (&gav)[8]) {
;     const int t0 = 64 * tile;
; #pragma unroll
;     for (int i = 0; i < 4; ++i) {
;       const int ci = tid + 256 * i; const int row = ci >> 4, ch = ci & 15;
;       *(u32x4*)(XC + row * 136 + 8 * ch) = xin[i];
;     }
;     float gcur[8];
; #pragma unroll
;     for (int i = 0; i < 8; ++i) gcur[i] = bf2f(gav[i]);
;     __syncthreads();
;     flush_y();
;     ...
;     float hin = CARRY[sc];
; #pragma unroll
;     for (int s2 = 0; s2 < 7; ++s2)
;       if (s2 < ssg) hin = SEGA[s2 * 32 + sc] * hin + SEGH[s2 * 32 + sc];
;     __syncthreads();
;     {
;       float h = hin;
; #pragma unroll
;       for (int i = 0; i < 8; ++i) {
;         const float a = AUa[(8 * ssg + i) * 33 + sc], uu = AUu[(8 * ssg + i) * 33 + sc];
;         h = a * h + uu;
;         const int t = t0 + 8 * ssg + i;
;         ypend[i] = f2bf(h * siluf_(gcur[i]));
;       }
;       if (ssg == 7) CARRY[sc] = h;
;       ypend_t0 = t0;
.LBB0_1460:
	s_or_b64 exec, exec, s[4:5]
	s_waitcnt lgkmcnt(0)
	s_barrier
	ds_read2_b32 v[14:15], v137 offset1:33
	ds_read2_b32 v[56:57], v138 offset0:64 offset1:97
	s_waitcnt lgkmcnt(0)
	v_fma_f32 v56, v13, v14, v56
	v_fmac_f32_e32 v57, v56, v15
	ds_read2_b32 v[14:15], v137 offset0:66 offset1:99
	ds_read2_b32 v[54:55], v138 offset0:130 offset1:163
	s_waitcnt lgkmcnt(0)
	v_fma_f32 v54, v57, v14, v54
	v_fmac_f32_e32 v55, v54, v15
	ds_read2_b32 v[14:15], v137 offset0:132 offset1:165
	ds_read2_b32 v[52:53], v138 offset0:196 offset1:229
	s_waitcnt lgkmcnt(0)
	v_fma_f32 v52, v55, v14, v52
	v_fmac_f32_e32 v53, v52, v15
	ds_read2_b32 v[58:59], v137 offset0:198 offset1:231
	ds_read2_b32 v[14:15], v140 offset0:6 offset1:39
	s_waitcnt lgkmcnt(0)
	v_fma_f32 v13, v53, v58, v14
	v_fmac_f32_e32 v15, v13, v59
	s_and_saveexec_b64 s[4:5], s[50:51]
	ds_write_b32 v115, v15 offset:53760
	s_or_b64 exec, exec, s[4:5]
	v_lshlrev_b32_e32 v14, 16, v120
	v_mul_f32_e32 v58, 0xbfb8aa3b, v14
	v_exp_f32_e32 v58, v58
	v_lshlrev_b32_e32 v59, 16, v119
	v_lshlrev_b32_e32 v60, 16, v122
	v_lshlrev_b32_e32 v61, 16, v121
	v_add_f32_e32 v58, 1.0, v58
	v_rcp_f32_e32 v58, v58
	v_lshlrev_b32_e32 v62, 16, v124
	v_lshlrev_b32_e32 v63, 16, v123
	v_lshlrev_b32_e32 v64, 16, v128
	v_mul_f32_e32 v14, v58, v14
	v_mul_f32_e32 v14, v14, v56
	v_cvt_pk_bf16_f32 v58, v14, s0
	v_mul_f32_e32 v14, 0xbfb8aa3b, v59
	v_exp_f32_e32 v14, v14
	v_lshlrev_b32_e32 v65, 16, v127
	s_cmp_gt_u32 s7, 32
	v_add_f32_e32 v14, 1.0, v14
	v_rcp_f32_e32 v14, v14
	s_nop 0
	v_mul_f32_e32 v14, v14, v59
	v_mul_f32_e32 v14, v14, v57
	v_cvt_pk_bf16_f32 v59, v14, s0
	v_mul_f32_e32 v14, 0xbfb8aa3b, v60
	v_exp_f32_e32 v14, v14
	s_nop 0
	v_add_f32_e32 v14, 1.0, v14
	v_rcp_f32_e32 v14, v14
	s_nop 0
	v_mul_f32_e32 v14, v14, v60
	v_mul_f32_e32 v14, v14, v54
	v_cvt_pk_bf16_f32 v56, v14, s0
	v_mul_f32_e32 v14, 0xbfb8aa3b, v61
	v_exp_f32_e32 v14, v14
	s_nop 0
	v_add_f32_e32 v14, 1.0, v14
	v_rcp_f32_e32 v14, v14
	s_nop 0
	v_mul_f32_e32 v14, v14, v61
	v_mul_f32_e32 v14, v14, v55
	v_cvt_pk_bf16_f32 v57, v14, s0
	v_mul_f32_e32 v14, 0xbfb8aa3b, v62
	v_exp_f32_e32 v14, v14
	s_nop 0
	v_add_f32_e32 v14, 1.0, v14
	v_rcp_f32_e32 v14, v14
	s_nop 0
	v_mul_f32_e32 v14, v14, v62
	v_mul_f32_e32 v14, v14, v52
	v_cvt_pk_bf16_f32 v54, v14, s0
	v_mul_f32_e32 v14, 0xbfb8aa3b, v63
	v_exp_f32_e32 v14, v14
	s_nop 0
	v_add_f32_e32 v14, 1.0, v14
	v_rcp_f32_e32 v14, v14
	s_nop 0
	v_mul_f32_e32 v14, v14, v63
	v_mul_f32_e32 v14, v14, v53
	v_cvt_pk_bf16_f32 v55, v14, s0
	v_mul_f32_e32 v14, 0xbfb8aa3b, v64
	v_exp_f32_e32 v14, v14
	s_nop 0
	v_add_f32_e32 v14, 1.0, v14
	v_rcp_f32_e32 v14, v14
	s_nop 0
	v_mul_f32_e32 v14, v14, v64
	v_mul_f32_e32 v13, v14, v13
	v_cvt_pk_bf16_f32 v14, v13, s0
	v_mul_f32_e32 v13, 0xbfb8aa3b, v65
	v_exp_f32_e32 v13, v13
	s_nop 0
	v_add_f32_e32 v13, 1.0, v13
	v_rcp_f32_e32 v13, v13
	s_nop 0
	v_mul_f32_e32 v13, v13, v65
	v_mul_f32_e32 v13, v13, v15
	v_cvt_pk_bf16_f32 v15, v13, s0
	s_cbranch_scc1 .LBB0_1554
	v_add_u32_e32 v60, s6, v83
	v_cmp_gt_i32_e64 s[52:53], s15, v60
	v_add_u32_e32 v52, s6, v69
	s_waitcnt vmcnt(8)
	ds_write_b128 v106, v[36:39]
	ds_write_b128 v107, v[40:43]
	ds_write_b128 v109, v[44:47]
	ds_write_b128 v110, v[48:51]
	s_waitcnt lgkmcnt(0)
	s_barrier
	s_and_saveexec_b64 s[4:5], s[52:53]
	s_cbranch_execz .LBB0_1465
	v_ashrrev_i32_e32 v53, 31, v52
	v_lshlrev_b64 v[62:63], 11, v[52:53]
	v_lshl_add_u64 v[62:63], v[74:75], 0, v[62:63]
	global_store_short v[62:63], v58, off

; __device__ __forceinline__ void rglru_unit(const Params& p, const WS& ws, int j, int u, bool dry = false) {
;     ...
;   auto prefetch = [&](int tile, u32x4 (&xin)[4], bf16_t (&gav)[8]) {
;     const int t0 = 64 * tile;
; #pragma unroll
;     for (int i = 0; i < 4; ++i) {
;       const int ci = tid + 256 * i; const int row = ci >> 4, ch = ci & 15; const int t = t0 + row;
;       xin[i] = (u32x4){0, 0, 0, 0};
;       if (t < T_) xin[i] = *(const u32x4*)(ws.XA + (size_t)(b * T_ + t) * 1024 + 128 * g + 8 * ch);
;     }
; #pragma unroll
;     for (int i = 0; i < 8; ++i) {
;       const int t = t0 + 8 * ssg + i;
;       gav[i] = 0;
;       if (t < T_) gav[i] = ws.GA[(size_t)(b * T_ + t) * 1024 + 128 * g + 32 * jq + sc];
;     }
;   };
.LBB0_1479:
	s_or_b64 exec, exec, s[4:5]
	s_cmp_eq_u32 s101, 1
	s_cbranch_scc0 .Lrg_g2_skip
	s_waitcnt vmcnt(8)
	v_mov_b32_e32 v94, v151
	v_mov_b32_e32 v92, v152
	v_mov_b32_e32 v90, v149
	v_mov_b32_e32 v91, v150
	v_mov_b32_e32 v87, v147
	v_mov_b32_e32 v86, v243
	v_mov_b32_e32 v85, v146
	v_mov_b32_e32 v88, v148
	s_mov_b32 s101, 0
.Lrg_g2_skip:
	s_cmp_gt_u32 s7, 30
	v_mov_b32_e32 v151, v94
	v_mov_b32_e32 v152, v92
	v_mov_b32_e32 v149, v90
	v_mov_b32_e32 v150, v91
	v_mov_b32_e32 v147, v87
	v_mov_b32_e32 v243, v86
	v_mov_b32_e32 v146, v85
	v_mov_b32_e32 v148, v88
	s_cbranch_scc1 .LBB0_1505
	s_cmpk_gt_i32 s6, 0x710
	s_cbranch_scc1 .Lrg_pslow2
	v_add_u32_e32 v14, s6, v118
	v_add_u32_e32 v14, 0xc0, v14
	v_ashrrev_i32_e32 v15, 31, v14
	v_lshlrev_b64 v[14:15], 11, v[14:15]
	v_lshl_add_u64 v[14:15], v[76:77], 0, v[14:15]
	global_load_dwordx4 v[36:39], v[14:15], off
	v_add_u32_e32 v14, s6, v117
	v_add_u32_e32 v14, 0xc0, v14
	v_ashrrev_i32_e32 v15, 31, v14
	v_lshlrev_b64 v[14:15], 11, v[14:15]
	v_lshl_add_u64 v[14:15], v[76:77], 0, v[14:15]
	global_load_dwordx4 v[40:43], v[14:15], off
	v_add_u32_e32 v14, s6, v116
	v_add_u32_e32 v14, 0xc0, v14
	v_ashrrev_i32_e32 v15, 31, v14
	v_lshlrev_b64 v[14:15], 11, v[14:15]
	v_lshl_add_u64 v[14:15], v[76:77], 0, v[14:15]
	global_load_dwordx4 v[44:47], v[14:15], off
	v_add_u32_e32 v14, s6, v71
	v_add_u32_e32 v14, 0xc0, v14
	v_ashrrev_i32_e32 v15, 31, v14
	v_lshlrev_b64 v[14:15], 11, v[14:15]
	v_lshl_add_u64 v[14:15], v[76:77], 0, v[14:15]
	global_load_dwordx4 v[48:51], v[14:15], off
	v_add_u32_e32 v14, 0xc0, v52
	v_ashrrev_i32_e32 v15, 31, v14
	v_lshlrev_b64 v[14:15], 11, v[14:15]
	v_lshl_add_u64 v[14:15], v[74:75], 0, v[14:15]
	global_load_ushort v243, v[14:15], off
	v_add_u32_e32 v14, 0xc1, v52
	v_ashrrev_i32_e32 v15, 31, v14
	v_lshlrev_b64 v[14:15], 11, v[14:15]
	v_lshl_add_u64 v[14:15], v[74:75], 0, v[14:15]
	global_load_ushort v146, v[14:15], off
	v_add_u32_e32 v14, 0xc2, v52
	v_ashrrev_i32_e32 v15, 31, v14
	v_lshlrev_b64 v[14:15], 11, v[14:15]
	v_lshl_add_u64 v[14:15], v[74:75], 0, v[14:15]
	global_load_ushort v148, v[14:15], off
	v_add_u32_e32 v14, 0xc3, v52
	v_ashrrev_i32_e32 v15, 31, v14
	v_lshlrev_b64 v[14:15], 11, v[14:15]
	v_lshl_add_u64 v[14:15], v[74:75], 0, v[14:15]
	global_load_ushort v147, v[14:15], off
	v_add_u32_e32 v14, 0xc4, v52
	v_ashrrev_i32_e32 v15, 31, v14
	v_lshlrev_b64 v[14:15], 11, v[14:15]
	v_lshl_add_u64 v[14:15], v[74:75], 0, v[14:15]
	global_load_ushort v150, v[14:15], off
	v_add_u32_e32 v14, 0xc5, v52
	v_ashrrev_i32_e32 v15, 31, v14
	v_lshlrev_b64 v[14:15], 11, v[14:15]
	v_lshl_add_u64 v[14:15], v[74:75], 0, v[14:15]
	global_load_ushort v149, v[14:15], off
	v_add_u32_e32 v14, 0xc6, v52
	v_ashrrev_i32_e32 v15, 31, v14
	v_lshlrev_b64 v[14:15], 11, v[14:15]
	v_lshl_add_u64 v[14:15], v[74:75], 0, v[14:15]
	global_load_ushort v152, v[14:15], off
	v_add_u32_e32 v14, 0xc7, v52
	v_ashrrev_i32_e32 v15, 31, v14
	v_lshlrev_b64 v[14:15], 11, v[14:15]
	v_lshl_add_u64 v[14:15], v[74:75], 0, v[14:15]
	global_load_ushort v151, v[14:15], off
	s_branch .LBB0_1505
.Lrg_pslow2:
	v_add_u32_e32 v13, s6, v79
	v_mov_b32_e32 v40, v12
	v_mov_b32_e32 v41, v12
	v_add_u32_e32 v13, 0xc0, v13
	v_mov_b32_e32 v42, v12
	v_mov_b32_e32 v43, v12
	v_mov_b64_e32 v[36:37], v[40:41]
	v_cmp_gt_i32_e64 s[52:53], s15, v13
	v_mov_b64_e32 v[38:39], v[42:43]
	s_and_saveexec_b64 s[4:5], s[52:53]
	s_cbranch_execz .LBB0_1482
	v_add_u32_e32 v13, s6, v118
	v_add_u32_e32 v14, 0xc0, v13
	v_ashrrev_i32_e32 v15, 31, v14
	v_lshlrev_b64 v[14:15], 11, v[14:15]
	v_lshl_add_u64 v[14:15], v[76:77], 0, v[14:15]
	global_load_dwordx4 v[36:39], v[14:15], off

; __device__ __forceinline__ void rglru_unit(const Params& p, const WS& ws, int j, int u, bool dry = false) {
;     ...
; #pragma unroll
;     for (int i = 0; i < 8; ++i) {
;       const int t = t0 + 8 * ssg + i;
;       gav[i] = 0;
;       if (t < T_) gav[i] = ws.GA[(size_t)(b * T_ + t) * 1024 + 128 * g + 32 * jq + sc];
;     }
.LBB0_1488:
	s_or_b64 exec, exec, s[4:5]
	v_add_u32_e32 v13, 0xc0, v60
	v_cmp_gt_i32_e64 s[52:53], s15, v13
	v_mov_b32_e32 v146, 0
	v_mov_b32_e32 v243, 0
	s_and_saveexec_b64 s[4:5], s[52:53]
	s_cbranch_execz .LBB0_1490
	v_add_u32_e32 v14, 0xc0, v52
	v_ashrrev_i32_e32 v15, 31, v14
	v_lshlrev_b64 v[14:15], 11, v[14:15]
	v_lshl_add_u64 v[14:15], v[74:75], 0, v[14:15]
	global_load_ushort v243, v[14:15], off

; __device__ __forceinline__ void rglru_unit(const Params& p, const WS& ws, int j, int u, bool dry = false) {
;     ...
; #pragma unroll 1
;   for (int tile = 0; tile < 33; tile += 2) {
;     body(tile, xinA, gavA);
;     if (tile + 1 < 33) body(tile + 1, xinB, gavB);
;   }
.LBB0_1554:
	s_lshl_b32 s4, s12, 6
	v_mov_b32_e32 v151, v94
	v_mov_b32_e32 v152, v92
	v_mov_b32_e32 v149, v90
	v_mov_b32_e32 v150, v91
	v_mov_b32_e32 v147, v87
	v_mov_b32_e32 v243, v86
	v_mov_b32_e32 v146, v85
	v_mov_b32_e32 v148, v88
.LBB0_1555:
	s_add_i32 s12, s12, 2
	s_addk_i32 s6, 0x80
	s_add_i32 s7, s7, 2
	s_cmp_gt_u32 s13, 30
	s_cbranch_scc1 .LBB0_1563
	s_cmpk_gt_i32 s6, 0x710
	s_cbranch_scc1 .Lrg_be_slow
	s_waitcnt vmcnt(20)
	v_mov_b32_e32 v127, v133
	v_mov_b32_e32 v128, v134
	v_mov_b32_e32 v123, v131
	v_mov_b32_e32 v124, v132
	v_mov_b32_e32 v121, v129
	v_mov_b32_e32 v122, v130
	v_mov_b32_e32 v119, v125
	v_mov_b32_e32 v120, v126
	s_mov_b32 s101, 1
	s_branch .LBB0_1376
.Lrg_be_slow:
	s_waitcnt vmcnt(0)
	v_mov_b32_e32 v127, v133
	v_mov_b32_e32 v128, v134
	v_mov_b32_e32 v123, v131
	v_mov_b32_e32 v124, v132
	v_mov_b32_e32 v121, v129
	v_mov_b32_e32 v122, v130
	v_mov_b32_e32 v119, v125
	v_mov_b32_e32 v120, v126
	v_mov_b32_e32 v94, v151
	v_mov_b32_e32 v92, v152
	v_mov_b32_e32 v90, v149
	v_mov_b32_e32 v91, v150
	v_mov_b32_e32 v87, v147
	v_mov_b32_e32 v86, v243
	v_mov_b32_e32 v85, v146
	v_mov_b32_e32 v88, v148
	s_mov_b32 s101, 0
	s_branch .LBB0_1376

; __device__ __forceinline__ int opaque_tid() { int t = threadIdx.x & 255; asm volatile("" : "+v"(t)); return t; }
; __device__ __forceinline__ void gla_unit(const Params& p, const WS& ws, int u, bool dry = false) {
;     ...
;   const int tid = opaque_tid(), lane = tid & 63, w = tid >> 6, lr = lane & 15, lq = lane >> 4;
;   for (int i = tid; i < 32 * 136 / 2; i += 256) ((unsigned*)STs)[i] = 0u;
;   f32x4 sacc[2][2];
; #pragma unroll
;   for (int a = 0; a < 2; ++a)
; #pragma unroll
;     for (int bb = 0; bb < 2; ++bb) sacc[a][bb] = (f32x4){0.f, 0.f, 0.f, 0.f};
;   u32x4 qrA[4], krA[4], vrA, qrB[4], krB[4], vrB;
;   float eblA[2], eblB[2];
;   const float* BLp = ws.BL + (size_t)((b * 4 + hd) * 33) * 128;
;   auto prefetch = [&](int c, u32x4 (&qr)[4], u32x4 (&kr)[4], u32x4& vr, float (&ebl)[2]) {
;     const int tbase = 64 * c - 48;
; #pragma unroll
;     for (int i = 0; i < 4; ++i) {
;       const int ci = tid + 256 * i; const int row = ci >> 4, ch = ci & 15; const int t = tbase + row;
;       qr[i] = (u32x4){0, 0, 0, 0}; kr[i] = (u32x4){0, 0, 0, 0};
;       if (t >= 0) {
;         qr[i] = *(const u32x4*)(ws.Q + (size_t)(b * T_ + t) * 512 + hd * 128 + ch * 8);
;         kr[i] = *(const u32x4*)(ws.K + (size_t)(b * T_ + t) * 512 + hd * 128 + ch * 8);
;       }
;     }
;     {
;       const int row = tid >> 2, ch = tid & 3; const int t = tbase + row;
;       vr = (u32x4){0, 0, 0, 0};
;       if (t >= 0) vr = *(const u32x4*)(ws.V + (size_t)(b * T_ + t) * 1024 + hd * 256 + sl * 32 + ch * 8);
;     }
;     ebl[0] = BLp[c * 128 + 16 * (2 * w) + lr];
;     ebl[1] = BLp[c * 128 + 16 * (2 * w + 1) + lr];
;   };
;   prefetch(0, qrA, krA, vrA, eblA);
;   prefetch(1, qrB, krB, vrB, eblB);
;   __syncthreads();
.LBB0_1606:
	s_or_b64 exec, exec, s[4:5]
	global_load_dword v204, v[6:7], off offset:512
	global_load_dword v179, v[6:7], off offset:576
	global_load_dword v209, v[6:7], off offset:512
	global_load_dword v242, v[6:7], off offset:576
	v_and_b32_e32 v14, 0x78, v11
	v_mul_lo_u32 v7, v131, s19
	v_lshlrev_b32_e32 v6, 1, v14
	v_mul_u32_u24_e32 v14, 0x48, v14
	v_add3_u32 v147, s37, v7, v6
	v_bitop3_b32 v7, v11, v131, 56 bitop3:0x6c
	v_lshlrev_b32_e32 v14, 1, v14
	v_add_u32_e32 v86, s37, v14
	v_lshlrev_b32_e32 v7, 1, v7
	v_add_u32_e32 v148, v86, v7
	v_add3_u32 v149, s37, v7, v14
	v_mul_lo_u32 v7, v142, s19
	v_add3_u32 v150, s37, v7, v6
	v_bitop3_b32 v7, v11, v142, 56 bitop3:0x6c
	v_lshlrev_b32_e32 v7, 1, v7
	v_add_u32_e32 v151, v86, v7
	v_add3_u32 v152, s37, v7, v14
	v_mul_lo_u32 v7, v143, s19
	v_add3_u32 v153, s37, v7, v6
	v_bitop3_b32 v7, v11, v143, 56 bitop3:0x6c
	v_lshlrev_b32_e32 v7, 1, v7
	v_add_u32_e32 v154, v86, v7
	v_add3_u32 v155, s37, v7, v14
	v_mul_lo_u32 v7, v144, s19
	v_add3_u32 v156, s37, v7, v6
	v_bitop3_b32 v7, v11, v144, 56 bitop3:0x6c
	v_lshlrev_b32_e32 v7, 1, v7
	v_add_u32_e32 v157, v86, v7
	v_add3_u32 v158, s37, v7, v14
	v_xor_b32_e32 v7, v8, v145
	v_mul_u32_u24_e32 v11, 0x48, v8
	v_bfe_u32 v15, v84, 4, 2
	v_lshlrev_b32_e32 v11, 1, v11
	v_lshlrev_b32_e32 v7, 1, v7
	v_add3_u32 v159, s37, v11, v7
	v_add3_u32 v160, s37, v7, v11
	v_lshlrev_b32_e32 v7, 4, v15
	v_lshl_or_b32 v161, v85, 4, v10
	v_add_u32_e32 v86, s37, v7
	v_mad_u64_u32 v[128:129], s[6:7], v161, s19, v[86:87]
	v_cmp_lt_i32_e32 vcc, -1, v85
	v_cmp_lt_i32_e64 s[38:39], 0, v85
	v_cmp_lt_i32_e64 s[40:41], 1, v85
	v_cmp_lt_i32_e64 s[42:43], 2, v85
	v_mul_u32_u24_e32 v85, 0x88, v10
	v_lshl_add_u32 v129, v85, 1, v86
	v_and_b32_e32 v86, 64, v191
	v_xor_b32_e32 v85, 16, v191
	v_add_u32_e32 v86, 64, v86
	v_cmp_lt_i32_e64 s[44:45], v85, v86
	s_movk_i32 s3, 0x90
	v_lshlrev_b32_e32 v14, 3, v15
	v_cndmask_b32_e64 v85, v191, v85, s[44:45]
	v_lshlrev_b32_e32 v163, 2, v85
	v_xor_b32_e32 v85, 32, v191
	v_cmp_lt_i32_e64 s[44:45], v85, v86
	v_bitop3_b32 v88, v4, v14, 40 bitop3:0x6c
	v_or_b32_e32 v13, 16, v10
	v_cndmask_b32_e64 v85, v191, v85, s[44:45]
	v_lshlrev_b32_e32 v168, 2, v85
	v_mul_lo_u32 v85, v4, s3
	v_add_u32_e32 v85, s37, v85
	v_lshl_add_u32 v169, v88, 1, v85
	v_mov_b32_e32 v88, s37
	v_mad_u32_u24 v88, v10, s3, v88
	v_bitop3_b32 v90, v10, 24, 16 bitop3:0xc8
	v_lshlrev_b32_e32 v130, 2, v15
	v_lshlrev_b32_e32 v10, 7, v10
	v_add3_u32 v176, v88, v10, v7
	v_or_b32_e32 v10, 16, v130
	v_cmp_gt_i32_e64 s[54:55], v10, v161
	v_cmp_lt_i32_e64 s[56:57], v10, v161
	v_or_b32_e32 v10, 18, v130
	v_cmp_gt_i32_e64 s[58:59], v10, v161
	v_or_b32_e32 v10, 19, v130
	v_cmp_gt_i32_e64 s[60:61], v10, v161
	v_or_b32_e32 v10, 32, v130
	v_cmp_gt_i32_e64 s[62:63], v10, v161
	v_cmp_lt_i32_e64 s[64:65], v10, v161
	v_or_b32_e32 v10, 34, v130
	v_cmp_gt_i32_e64 s[66:67], v10, v161
	v_or_b32_e32 v10, 35, v130
	s_add_u32 s4, s8, 0xe445000
	v_cmp_gt_i32_e64 s[68:69], v10, v161
	v_or_b32_e32 v10, 48, v130
	s_addc_u32 s5, s9, 0
	s_add_i32 s36, s37, 0x10400
	v_mul_lo_u32 v87, v161, s3
	v_cmp_gt_i32_e64 s[70:71], v10, v161
	v_cmp_lt_i32_e64 s[72:73], v10, v161
	v_or_b32_e32 v10, 50, v130
	v_add_u32_e32 v87, s36, v87
	v_cmp_gt_i32_e64 s[74:75], v10, v161
	v_or_b32_e32 v10, 51, v130
	v_cmp_gt_i32_e64 s[76:77], v10, v161
	v_add_u32_e32 v177, v87, v7
	v_mul_u32_u24_e32 v7, 0x440, v15
	v_lshlrev_b32_e32 v10, 1, v4
	s_lshl_b32 s36, s10, 3
	v_add3_u32 v178, s37, v7, v10
	v_or_b32_e32 v7, 16, v4
	s_lshl_b32 s6, s10, 5
	v_mul_lo_u32 v10, v7, s3
	s_add_u32 s6, s4, s6
	v_and_b32_e32 v89, 8, v84
	v_bitop3_b32 v84, v14, v84, 8 bitop3:0x78
	v_add_u32_e32 v10, s37, v10
	s_addc_u32 s7, s5, 0
	s_lshl_b32 s37, s34, 2
	v_lshl_add_u32 v170, v84, 1, v88
	v_add_u32_e32 v84, 0x900, v88
	v_bitop3_b32 v13, v14, v13, 24 bitop3:0x78
	s_add_u32 s6, s6, s37
	v_lshl_add_u32 v171, v13, 1, v84
	v_or_b32_e32 v13, 32, v14
	s_addc_u32 s7, s7, 0
	s_lshl_b32 s37, s10, 8
	v_cmp_eq_u32_e64 s[44:45], 0, v15
	v_bitop3_b32 v15, v7, v14, 56 bitop3:0x6c
	v_bitop3_b32 v7, v7, v13, 56 bitop3:0x6c
	s_add_u32 s12, s12, s37
	v_and_b32_e32 v86, 40, v4
	v_lshl_add_u32 v181, v7, 1, v10
	s_addc_u32 s13, s13, 0
	v_mov_b32_e32 v7, v12
	v_bitop3_b32 v86, v14, v86, 32 bitop3:0x36
	v_lshl_add_u64 v[132:133], s[12:13], 0, v[6:7]
	s_add_u32 s12, s80, s37
	s_mulk_i32 s11, 0x84
	s_mul_i32 s10, s10, 33
	v_lshl_add_u32 v172, v86, 1, v85
	v_bitop3_b32 v85, v14, v89, 32 bitop3:0x36
	s_addc_u32 s13, s81, 0
	s_add_i32 s10, s11, s10
	v_lshl_add_u32 v173, v85, 1, v88
	v_bitop3_b32 v85, v14, v90, 32 bitop3:0x36
	s_ashr_i32 s11, s10, 31
	v_lshl_add_u32 v174, v85, 1, v84
	v_or_b32_e32 v84, 2, v130
	s_lshl_b64 s[10:11], s[10:11], 9
	v_cmp_gt_i32_e64 s[50:51], v84, v161
	v_or_b32_e32 v84, 3, v130
	s_add_u32 s8, s8, s10
	v_cmp_gt_i32_e64 s[52:53], v84, v161
	v_lshl_add_u64 v[84:85], v[126:127], 1, s[96:97]
	s_addc_u32 s9, s9, s11
	v_subrev_u32_e32 v162, 48, v161
	v_lshl_add_u32 v180, v15, 1, v10
	v_lshl_add_u64 v[84:85], v[124:125], 1, v[84:85]
	v_mov_b32_e32 v15, v12
	v_lshl_add_u64 v[4:5], v[4:5], 2, s[8:9]
	s_mov_b64 s[8:9], 0xe649400
	v_mov_b32_e32 v10, 0
	s_mov_b32 s35, 1
	v_mov_b32_e32 v11, -1
	s_mov_b32 s92, 0
	v_cmp_gt_i32_e64 s[46:47], v130, v161
	v_cmp_lt_i32_e64 s[48:49], v130, v161
	v_add_u32_e32 v182, v87, v14
	v_lshl_add_u64 v[134:135], s[12:13], 0, v[6:7]
	v_lshl_add_u64 v[136:137], v[8:9], 1, v[84:85]
	v_lshl_add_u64 v[138:139], v[84:85], 0, v[14:15]
	v_lshl_add_u64 v[140:141], v[4:5], 0, s[8:9]
	v_add_u32_e32 v183, v145, v146
	v_add_u32_e32 v184, v144, v146
	v_add_u32_e32 v185, v143, v146
	v_add_u32_e32 v201, v142, v146
	v_add_u32_e32 v202, v131, v146
	v_add_u32_e32 v203, v162, v146
	v_mov_b32_e32 v4, 0
	v_mov_b32_e32 v5, 0
	v_mov_b32_e32 v6, 0
	v_mov_b32_e32 v7, 0
	s_mov_b32 s37, 0
	v_mov_b32_e32 v92, 0
	v_mov_b32_e32 v93, v10
	v_mov_b32_e32 v94, v10
	v_mov_b32_e32 v95, v10
	v_mov_b32_e32 v96, 0
	v_mov_b32_e32 v97, v10
	v_mov_b32_e32 v98, v10
	v_mov_b32_e32 v99, v10
	v_mov_b32_e32 v88, 0
	v_mov_b32_e32 v89, v10
	v_mov_b32_e32 v90, v10
	v_mov_b32_e32 v91, v10
	v_mov_b32_e32 v84, 0
	v_mov_b32_e32 v85, v10
	v_mov_b32_e32 v86, v10
	v_mov_b32_e32 v87, v10
	s_waitcnt vmcnt(0) lgkmcnt(0)
	s_barrier
; __device__ __forceinline__ void gla_unit(const Params& p, const WS& ws, int u, bool dry = false) {
;     ...
;   auto prefetch = [&](int c, u32x4 (&qr)[4], u32x4 (&kr)[4], u32x4& vr, float (&ebl)[2]) {
;     const int tbase = 64 * c - 48;
; #pragma unroll
;     for (int i = 0; i < 4; ++i) {
;       const int ci = tid + 256 * i; const int row = ci >> 4, ch = ci & 15; const int t = tbase + row;
;       qr[i] = (u32x4){0, 0, 0, 0}; kr[i] = (u32x4){0, 0, 0, 0};
;       if (t >= 0) {
;         qr[i] = *(const u32x4*)(ws.Q + (size_t)(b * T_ + t) * 512 + hd * 128 + ch * 8);
;         kr[i] = *(const u32x4*)(ws.K + (size_t)(b * T_ + t) * 512 + hd * 128 + ch * 8);
;       }
;     }
;     {
;       const int row = tid >> 2, ch = tid & 3; const int t = tbase + row;
;       vr = (u32x4){0, 0, 0, 0};
;       if (t >= 0) vr = *(const u32x4*)(ws.V + (size_t)(b * T_ + t) * 1024 + hd * 256 + sl * 32 + ch * 8);
;     }
;     ebl[0] = BLp[c * 128 + 16 * (2 * w) + lr];
;     ebl[1] = BLp[c * 128 + 16 * (2 * w + 1) + lr];
;   };
;     ...
;   auto body = [&](int c, u32x4 (&qr)[4], u32x4 (&kr)[4], u32x4& vr, float (&ebl)[2]) {
; #pragma unroll
;     for (int i = 0; i < 4; ++i) {
;       const int ci = tid + 256 * i; const int row = ci >> 4, ch = ci & 15;
;       *(u32x4*)(QDs + row * 136 + ch * 8) = qr[i];
;       *(u32x4*)(KIs + row * 136 + ch * 8) = kr[i];
;       const unsigned kk[4] = {kr[i].x, kr[i].y, kr[i].z, kr[i].w};
; #pragma unroll
;       for (int e = 0; e < 4; ++e) {
;         KIT[(ch * 8 + 2 * e) * 72 + (row ^ ((ch & 7) << 3))] = (bf16_t)(kk[e] & 0xffffu);
;         KIT[(ch * 8 + 2 * e + 1) * 72 + (row ^ ((ch & 7) << 3))] = (bf16_t)(kk[e] >> 16);
;       }
;     }
;     {
;       const int row = tid >> 2, ch = tid & 3;
;       const unsigned vv[4] = {vr.x, vr.y, vr.z, vr.w};
; #pragma unroll
;       for (int e = 0; e < 4; ++e) {
;         VTs[(ch * 8 + 2 * e) * 72 + (row ^ (ch << 3))] = (bf16_t)(vv[e] & 0xffffu);
;         VTs[(ch * 8 + 2 * e + 1) * 72 + (row ^ (ch << 3))] = (bf16_t)(vv[e] >> 16);
;       }
;     }
;     const float eb0 = ebl[0], eb1 = ebl[1];
;     __syncthreads();
;     flush_o();
;     if (c + 2 < 33) prefetch(c + 2, qr, kr, vr, ebl);
.LBB0_1607:
	v_cmp_lt_i32_e64 s[80:81], -1, v11
	ds_write_b128 v147, v[28:31]
	ds_write_b128 v147, v[16:19] offset:17408
	ds_write_b16 v148, v16 offset:34816
	ds_write_b16_d16_hi v149, v16 offset:34960
	ds_write_b16 v148, v17 offset:35104
	ds_write_b16_d16_hi v148, v17 offset:35248
	ds_write_b16 v148, v18 offset:35392
	ds_write_b16_d16_hi v148, v18 offset:35536
	ds_write_b16 v148, v19 offset:35680
	ds_write_b16_d16_hi v148, v19 offset:35824
	ds_write_b128 v150, v[32:35]
	ds_write_b128 v150, v[20:23] offset:17408
	ds_write_b16 v151, v20 offset:34816
	ds_write_b16_d16_hi v152, v20 offset:34960
	ds_write_b16 v151, v21 offset:35104
	ds_write_b16_d16_hi v151, v21 offset:35248
	ds_write_b16 v151, v22 offset:35392
	ds_write_b16_d16_hi v151, v22 offset:35536
	ds_write_b16 v151, v23 offset:35680
	ds_write_b16_d16_hi v151, v23 offset:35824
	ds_write_b128 v153, v[36:39]
	ds_write_b128 v153, v[24:27] offset:17408
	ds_write_b16 v154, v24 offset:34816
	ds_write_b16_d16_hi v155, v24 offset:34960
	ds_write_b16 v154, v25 offset:35104
	ds_write_b16_d16_hi v154, v25 offset:35248
	ds_write_b16 v154, v26 offset:35392
	ds_write_b16_d16_hi v154, v26 offset:35536
	ds_write_b16 v154, v27 offset:35680
	ds_write_b16_d16_hi v154, v27 offset:35824
	ds_write_b128 v156, v[40:43]
	ds_write_b128 v156, v[60:63] offset:17408
	ds_write_b16 v157, v60 offset:34816
	ds_write_b16_d16_hi v158, v60 offset:34960
	ds_write_b16 v157, v61 offset:35104
	ds_write_b16_d16_hi v157, v61 offset:35248
	ds_write_b16 v157, v62 offset:35392
	ds_write_b16_d16_hi v157, v62 offset:35536
	ds_write_b16 v157, v63 offset:35680
	ds_write_b16_d16_hi v157, v63 offset:35824
	ds_write_b16 v159, v0 offset:53248
	ds_write_b16_d16_hi v160, v0 offset:53392
	ds_write_b16 v159, v1 offset:53536
	ds_write_b16_d16_hi v159, v1 offset:53680
	ds_write_b16 v159, v2 offset:53824
	ds_write_b16_d16_hi v159, v2 offset:53968
	ds_write_b16 v159, v3 offset:54112
	ds_write_b16_d16_hi v159, v3 offset:54256
	s_waitcnt lgkmcnt(0)
	s_barrier
	s_and_saveexec_b64 s[12:13], s[80:81]
	s_cbranch_execz .LBB0_1610
	v_add_u32_e32 v8, v11, v146
	v_ashrrev_i32_e32 v9, 31, v8
	v_lshlrev_b64 v[14:15], 11, v[8:9]
	v_lshl_add_u64 v[14:15], v[138:139], 0, v[14:15]
	global_store_dwordx2 v[14:15], v[4:5], off
	global_store_dwordx2 v[14:15], v[6:7], off offset:32
	s_and_b64 exec, exec, s[44:45]
	s_cbranch_execz .LBB0_1610
	v_lshlrev_b64 v[4:5], 7, v[8:9]
	v_lshl_add_u64 v[4:5], s[6:7], 0, v[4:5]
	global_store_dword v[4:5], v10, off
.LBB0_1610:
	s_or_b64 exec, exec, s[12:13]
	s_add_i32 s8, s35, -1
	s_cmp_gt_u32 s8, 30
	v_mov_b32_e32 v206, v207
	v_mov_b32_e32 v205, v208
	s_cbranch_scc1 .Lgla_skipA
	v_add_u32_e32 v100, s92, v202
	v_add_u32_e32 v100, 0x50, v100
	v_ashrrev_i32_e32 v101, 31, v100
	v_lshlrev_b64 v[100:101], 10, v[100:101]
	v_lshl_add_u64 v[14:15], v[132:133], 0, v[100:101]
	global_load_dwordx4 v[28:31], v[14:15], off
	v_lshl_add_u64 v[14:15], v[134:135], 0, v[100:101]
	global_load_dwordx4 v[16:19], v[14:15], off
	v_add_u32_e32 v100, s92, v201
	v_add_u32_e32 v100, 0x50, v100
	v_ashrrev_i32_e32 v101, 31, v100
	v_lshlrev_b64 v[100:101], 10, v[100:101]
	v_lshl_add_u64 v[14:15], v[132:133], 0, v[100:101]
	global_load_dwordx4 v[32:35], v[14:15], off
	v_lshl_add_u64 v[14:15], v[134:135], 0, v[100:101]
	global_load_dwordx4 v[20:23], v[14:15], off
	v_add_u32_e32 v100, s92, v185
	v_add_u32_e32 v100, 0x50, v100
	v_ashrrev_i32_e32 v101, 31, v100
	v_lshlrev_b64 v[100:101], 10, v[100:101]
	v_lshl_add_u64 v[14:15], v[132:133], 0, v[100:101]
	global_load_dwordx4 v[36:39], v[14:15], off
	v_lshl_add_u64 v[14:15], v[134:135], 0, v[100:101]
	global_load_dwordx4 v[24:27], v[14:15], off
	v_add_u32_e32 v100, s92, v184
	v_add_u32_e32 v100, 0x50, v100
	v_ashrrev_i32_e32 v101, 31, v100
	v_lshlrev_b64 v[100:101], 10, v[100:101]
	v_lshl_add_u64 v[14:15], v[132:133], 0, v[100:101]
	global_load_dwordx4 v[40:43], v[14:15], off
	v_lshl_add_u64 v[14:15], v[134:135], 0, v[100:101]
	global_load_dwordx4 v[60:63], v[14:15], off
	v_add_u32_e32 v100, s92, v183
	v_add_u32_e32 v100, 0x50, v100
	v_ashrrev_i32_e32 v101, 31, v100
	v_lshlrev_b64 v[100:101], 11, v[100:101]
	v_lshl_add_u64 v[14:15], v[136:137], 0, v[100:101]
	global_load_dwordx4 v[0:3], v[14:15], off
	global_load_dword v205, v[140:141], off
	global_load_dword v206, v[140:141], off offset:64

; __device__ __forceinline__ void gla_unit(const Params& p, const WS& ws, int u, bool dry = false) {
;     ...
;   auto body = [&](int c, u32x4 (&qr)[4], u32x4 (&kr)[4], u32x4& vr, float (&ebl)[2]) {
; #pragma unroll
;     for (int i = 0; i < 4; ++i) {
;       const int ci = tid + 256 * i; const int row = ci >> 4, ch = ci & 15;
;       *(u32x4*)(QDs + row * 136 + ch * 8) = qr[i];
;       *(u32x4*)(KIs + row * 136 + ch * 8) = kr[i];
;       const unsigned kk[4] = {kr[i].x, kr[i].y, kr[i].z, kr[i].w};
; #pragma unroll
;       for (int e = 0; e < 4; ++e) {
;         KIT[(ch * 8 + 2 * e) * 72 + (row ^ ((ch & 7) << 3))] = (bf16_t)(kk[e] & 0xffffu);
;     ...
; #pragma unroll
;     for (int ks = 0; ks < 4; ++ks)
; #pragma unroll
;       for (int mt = 0; mt < 2; ++mt) {
;         const bf16x8 sf = *(const bf16x8*)(STs + (16 * mt + lr) * 136 + 32 * ks + 8 * lq);
;         oacc[mt] = MFMA16(sf, xq[ks], oacc[mt]);
;       }
;     {
;       const int t = 64 * c - 48 + irow;
;       float sq = 0.f;
; #pragma unroll
;       for (int mt = 0; mt < 2; ++mt) sq += oacc[mt][0] * oacc[mt][0] + oacc[mt][1] * oacc[mt][1] + oacc[mt][2] * oacc[mt][2] + oacc[mt][3] * oacc[mt][3];
;       sq += __shfl_xor(sq, 16); sq += __shfl_xor(sq, 32);
;       tpend = t;
;       sqpend = sq;
; #pragma unroll
;       for (int mt = 0; mt < 2; ++mt) { opend[mt].x = cvt_pk_bf16(oacc[mt][0], oacc[mt][1]); opend[mt].y = cvt_pk_bf16(oacc[mt][2], oacc[mt][3]); }
;     }
;     __syncthreads();
; #pragma unroll
;     for (int ntl = 0; ntl < 2; ++ntl) {
; #pragma unroll
;       for (int ks = 0; ks < 2; ++ks) {
;         const bf16x8 kf = *(const bf16x8*)(KIT + (16 * (2 * w + ntl) + lr) * 72 + (((4 * ks + lq) ^ (((16 * (2 * w + ntl) + lr) >> 3) & 7)) << 3));
; #pragma unroll
;         for (int mt = 0; mt < 2; ++mt) {
;           const bf16x8 vf = *(const bf16x8*)(VTs + (16 * mt + lr) * 72 + (((4 * ks + lq) ^ (((16 * mt + lr) >> 3) & 3)) << 3));
;           sacc[mt][ntl] = MFMA16(vf, kf, sacc[mt][ntl]);
;         }
;       }
;       const float e = ntl ? eb1 : eb0;
; #pragma unroll
;       for (int mt = 0; mt < 2; ++mt) {
;         sacc[mt][ntl] = scale4(sacc[mt][ntl], e);
; #pragma unroll
;         for (int jj = 0; jj < 4; ++jj) STs[(16 * mt + 4 * lq + jj) * 136 + 16 * (2 * w + ntl) + lr] = f2bf(sacc[mt][ntl][jj]);
;       }
;     }
;     __syncthreads();
;   };
.LBB0_1634:
	s_or_b64 exec, exec, s[12:13]
	s_nop 1
	s_nop 0
	s_nop 0
	s_cmp_gt_u32 s35, 32
	s_waitcnt lgkmcnt(0)
	v_mfma_f32_16x16x32_bf16 v[108:111], v[212:215], v[104:107], v[116:119]
	s_waitcnt lgkmcnt(0)
	v_mfma_f32_16x16x32_bf16 v[104:107], v[216:219], v[104:107], v[120:123]
	s_nop 0
	s_waitcnt lgkmcnt(0)
	v_mfma_f32_16x16x32_bf16 v[108:111], v[220:223], v[100:103], v[108:111]
	s_nop 0
	s_waitcnt lgkmcnt(0)
	v_mfma_f32_16x16x32_bf16 v[100:103], v[224:227], v[100:103], v[104:107]
	s_nop 2
	s_nop 0
	s_waitcnt lgkmcnt(0)
	v_mfma_f32_16x16x32_bf16 v[104:107], v[228:231], v[8:11], v[108:111]
	s_nop 2
	s_nop 0
	s_waitcnt lgkmcnt(0)
	v_mfma_f32_16x16x32_bf16 v[8:11], v[232:235], v[8:11], v[100:103]
	s_nop 2
	s_nop 0
	s_waitcnt lgkmcnt(0)
	v_mfma_f32_16x16x32_bf16 v[100:103], v[244:247], v[4:7], v[104:107]
	s_nop 2
	s_nop 0
	s_waitcnt lgkmcnt(0)
	s_barrier
	v_mfma_f32_16x16x32_bf16 v[6:9], v[248:251], v[4:7], v[8:11]
	ds_read_b128 v[212:215], v169 offset:34816
	ds_read_b128 v[216:219], v170 offset:53248
	ds_read_b128 v[220:223], v171 offset:53248
	ds_read_b128 v[224:227], v172 offset:34816
	ds_read_b128 v[228:231], v173 offset:53248
	ds_read_b128 v[232:235], v174 offset:53248
	ds_read_b128 v[244:247], v180 offset:34816
	ds_read_b128 v[252:255], v181 offset:34816
	s_nop 2
	v_mov_b32_e32 v10, v101
	v_mov_b32_e32 v4, v100
	s_nop 2
	v_mov_b32_e32 v11, v7
	v_mov_b32_e32 v5, v6
	v_pk_mul_f32 v[10:11], v[10:11], v[10:11]
	v_cvt_pk_bf16_f32 v6, v6, v7
	v_pk_fma_f32 v[4:5], v[4:5], v[4:5], v[10:11]
	v_mov_b32_e32 v10, v102
	v_mov_b32_e32 v11, v8
	v_pk_fma_f32 v[4:5], v[10:11], v[10:11], v[4:5]
	v_mov_b32_e32 v10, v103
	v_mov_b32_e32 v11, v9
	v_pk_fma_f32 v[4:5], v[10:11], v[10:11], v[4:5]
	v_cvt_pk_bf16_f32 v7, v8, v9
	v_add_f32_e32 v4, v4, v5
	ds_bpermute_b32 v5, v163, v4
	v_mov_b32_e32 v8, v208
	s_waitcnt lgkmcnt(0)
	v_add_f32_e32 v4, v4, v5
	ds_bpermute_b32 v5, v168, v4
	s_waitcnt lgkmcnt(0)
	v_add_f32_e32 v10, v4, v5
	v_cvt_pk_bf16_f32 v4, v100, v101
	v_cvt_pk_bf16_f32 v5, v102, v103
	s_nop 0
	s_nop 0
	s_waitcnt lgkmcnt(0)
	v_mfma_f32_16x16x32_bf16 v[84:87], v[216:219], v[212:215], v[84:87]
	s_nop 0
	s_nop 0
	v_mfma_f32_16x16x32_bf16 v[96:99], v[220:223], v[212:215], v[96:99]
	s_nop 0
	s_nop 0
	s_nop 0
	v_mfma_f32_16x16x32_bf16 v[84:87], v[228:231], v[224:227], v[84:87]
	s_nop 0
	s_nop 0
	v_mfma_f32_16x16x32_bf16 v[96:99], v[232:235], v[224:227], v[96:99]
	s_nop 4
	v_mul_f32_e32 v84, v84, v8
	v_mul_f32_e32 v85, v85, v8
	v_mul_f32_e32 v86, v86, v8
	v_mul_f32_e32 v87, v87, v8
	s_nop 0
	v_cvt_pk_bf16_f32 v8, v84, s0
	ds_write_b16 v178, v8 offset:57856
	v_cvt_pk_bf16_f32 v8, v85, s0
	ds_write_b16 v178, v8 offset:58128
	v_cvt_pk_bf16_f32 v8, v86, s0
	ds_write_b16 v178, v8 offset:58400
	v_cvt_pk_bf16_f32 v8, v87, s0
	ds_write_b16 v178, v8 offset:58672
	s_nop 0
	v_mul_f32_e32 v96, v96, v208
	v_mul_f32_e32 v97, v97, v208
	v_mul_f32_e32 v98, v98, v208
	v_mul_f32_e32 v99, v99, v208
	s_nop 0
	v_cvt_pk_bf16_f32 v8, v96, s0
	ds_write_b16 v178, v8 offset:62208
	v_cvt_pk_bf16_f32 v8, v97, s0
	ds_write_b16 v178, v8 offset:62480
	v_cvt_pk_bf16_f32 v8, v98, s0
	ds_write_b16 v178, v8 offset:62752
	v_cvt_pk_bf16_f32 v8, v99, s0
	ds_write_b16 v178, v8 offset:63024
	s_nop 0
	s_nop 0
	s_nop 0
	v_mfma_f32_16x16x32_bf16 v[88:91], v[216:219], v[244:247], v[88:91]
	s_nop 0
	v_mov_b32_e32 v8, v207
	s_nop 0
	v_mfma_f32_16x16x32_bf16 v[92:95], v[220:223], v[244:247], v[92:95]
	s_nop 0
	s_nop 0
	s_nop 0
	v_mfma_f32_16x16x32_bf16 v[88:91], v[228:231], v[252:255], v[88:91]
	s_nop 0
	s_nop 0
	v_mfma_f32_16x16x32_bf16 v[92:95], v[232:235], v[252:255], v[92:95]
	s_nop 4
	v_mul_f32_e32 v88, v88, v8
	v_mul_f32_e32 v89, v89, v8
	v_mul_f32_e32 v90, v90, v8
	v_mul_f32_e32 v91, v91, v8
	s_nop 0
	v_cvt_pk_bf16_f32 v8, v88, s0
	ds_write_b16 v178, v8 offset:57888
	v_cvt_pk_bf16_f32 v8, v89, s0
	ds_write_b16 v178, v8 offset:58160
	v_cvt_pk_bf16_f32 v8, v90, s0
	ds_write_b16 v178, v8 offset:58432
	v_cvt_pk_bf16_f32 v8, v91, s0
	ds_write_b16 v178, v8 offset:58704
	s_nop 0
	v_mul_f32_e32 v92, v92, v207
	v_mul_f32_e32 v93, v93, v207
	v_mul_f32_e32 v94, v94, v207
	v_mul_f32_e32 v95, v95, v207
	s_nop 0
	v_cvt_pk_bf16_f32 v8, v92, s0
	ds_write_b16 v178, v8 offset:62240
	v_cvt_pk_bf16_f32 v8, v93, s0
	ds_write_b16 v178, v8 offset:62512
	v_cvt_pk_bf16_f32 v8, v94, s0
	ds_write_b16 v178, v8 offset:62784
	v_cvt_pk_bf16_f32 v8, v95, s0
	ds_write_b16 v178, v8 offset:63056
	s_waitcnt lgkmcnt(0)
	s_barrier
	s_cbranch_scc1 .LBB0_1663
	v_add_u32_e32 v207, s92, v161
	v_subrev_u32_e32 v8, 48, v207
	v_cmp_lt_i32_e64 s[80:81], -1, v8
	s_waitcnt vmcnt(13)
	ds_write_b128 v147, v[44:47]
	ds_write_b128 v147, v[48:51] offset:17408
	ds_write_b16 v148, v48 offset:34816
	ds_write_b16_d16_hi v149, v48 offset:34960
	ds_write_b16 v148, v49 offset:35104
	ds_write_b16_d16_hi v148, v49 offset:35248
	ds_write_b16 v148, v50 offset:35392
	ds_write_b16_d16_hi v148, v50 offset:35536
	ds_write_b16 v148, v51 offset:35680
	ds_write_b16_d16_hi v148, v51 offset:35824
	ds_write_b128 v150, v[56:59]
	ds_write_b128 v150, v[52:55] offset:17408
	ds_write_b16 v151, v52 offset:34816
	ds_write_b16_d16_hi v152, v52 offset:34960
	ds_write_b16 v151, v53 offset:35104
	ds_write_b16_d16_hi v151, v53 offset:35248
	ds_write_b16 v151, v54 offset:35392
	ds_write_b16_d16_hi v151, v54 offset:35536
	ds_write_b16 v151, v55 offset:35680
	ds_write_b16_d16_hi v151, v55 offset:35824
	ds_write_b128 v153, v[64:67]
	ds_write_b128 v153, v[68:71] offset:17408
	ds_write_b16 v154, v68 offset:34816
	ds_write_b16_d16_hi v155, v68 offset:34960
	ds_write_b16 v154, v69 offset:35104
	ds_write_b16_d16_hi v154, v69 offset:35248
	ds_write_b16 v154, v70 offset:35392
	ds_write_b16_d16_hi v154, v70 offset:35536
	ds_write_b16 v154, v71 offset:35680
	ds_write_b16_d16_hi v154, v71 offset:35824
	ds_write_b128 v156, v[72:75]
	ds_write_b128 v156, v[76:79] offset:17408
	ds_write_b16 v157, v76 offset:34816
	ds_write_b16_d16_hi v158, v76 offset:34960
	ds_write_b16 v157, v77 offset:35104
	ds_write_b16_d16_hi v157, v77 offset:35248
	ds_write_b16 v157, v78 offset:35392
	ds_write_b16_d16_hi v157, v78 offset:35536
	ds_write_b16 v157, v79 offset:35680
	ds_write_b16_d16_hi v157, v79 offset:35824
	ds_write_b16 v159, v80 offset:53248
	ds_write_b16_d16_hi v160, v80 offset:53392
	ds_write_b16 v159, v81 offset:53536
	ds_write_b16_d16_hi v159, v81 offset:53680
	ds_write_b16 v159, v82 offset:53824
	ds_write_b16_d16_hi v159, v82 offset:53968
	ds_write_b16 v159, v83 offset:54112
	ds_write_b16_d16_hi v159, v83 offset:54256
	s_waitcnt lgkmcnt(0)
	s_barrier
	s_and_saveexec_b64 s[12:13], s[80:81]
	s_cbranch_execz .LBB0_1638
	v_add_u32_e32 v8, s92, v203
	v_ashrrev_i32_e32 v9, 31, v8
	v_lshlrev_b64 v[14:15], 11, v[8:9]
	v_lshl_add_u64 v[14:15], v[138:139], 0, v[14:15]
	global_store_dwordx2 v[14:15], v[4:5], off
	global_store_dwordx2 v[14:15], v[6:7], off offset:32
	s_and_b64 exec, exec, s[44:45]
	s_cbranch_execz .LBB0_1638
	v_lshlrev_b64 v[4:5], 7, v[8:9]
	v_lshl_add_u64 v[4:5], s[6:7], 0, v[4:5]
	global_store_dword v[4:5], v10, off
; __device__ __forceinline__ void gla_unit(const Params& p, const WS& ws, int u, bool dry = false) {
;     ...
;   auto prefetch = [&](int c, u32x4 (&qr)[4], u32x4 (&kr)[4], u32x4& vr, float (&ebl)[2]) {
;     const int tbase = 64 * c - 48;
; #pragma unroll
;     for (int i = 0; i < 4; ++i) {
;       const int ci = tid + 256 * i; const int row = ci >> 4, ch = ci & 15; const int t = tbase + row;
;       qr[i] = (u32x4){0, 0, 0, 0}; kr[i] = (u32x4){0, 0, 0, 0};
;       if (t >= 0) {
;         qr[i] = *(const u32x4*)(ws.Q + (size_t)(b * T_ + t) * 512 + hd * 128 + ch * 8);
;         kr[i] = *(const u32x4*)(ws.K + (size_t)(b * T_ + t) * 512 + hd * 128 + ch * 8);
;       }
;     }
;     {
;       const int row = tid >> 2, ch = tid & 3; const int t = tbase + row;
;       vr = (u32x4){0, 0, 0, 0};
;       if (t >= 0) vr = *(const u32x4*)(ws.V + (size_t)(b * T_ + t) * 1024 + hd * 256 + sl * 32 + ch * 8);
;     }
;     ebl[0] = BLp[c * 128 + 16 * (2 * w) + lr];
;     ebl[1] = BLp[c * 128 + 16 * (2 * w + 1) + lr];
;   };
.LBB0_1638:
	s_or_b64 exec, exec, s[12:13]
	s_cmp_gt_u32 s35, 30
	s_waitcnt vmcnt(0)
	v_mov_b32_e32 v179, v242
	v_mov_b32_e32 v204, v209
	v_mov_b32_e32 v242, v179
	v_mov_b32_e32 v209, v204
	s_cbranch_scc1 .LBB0_1650
	v_add_u32_e32 v4, s92, v131
	v_mov_b32_e32 v14, v12
	v_mov_b32_e32 v15, v12
	v_mov_b32_e32 v52, v12
	v_mov_b32_e32 v53, v12
	v_add_u32_e32 v4, 0x90, v4
	v_mov_b32_e32 v13, v12
	v_mov_b32_e32 v54, v12
	v_mov_b32_e32 v55, v12
	v_mov_b64_e32 v[48:49], v[52:53]
	v_mov_b64_e32 v[46:47], v[14:15]
	v_cmp_lt_i32_e64 s[80:81], -1, v4
	v_mov_b64_e32 v[50:51], v[54:55]
	v_mov_b64_e32 v[44:45], v[12:13]
	s_and_saveexec_b64 s[12:13], s[80:81]
	s_cbranch_execz .LBB0_1641
	v_add_u32_e32 v4, s92, v202
	v_add_u32_e32 v4, 0x90, v4
	v_ashrrev_i32_e32 v5, 31, v4
	v_lshlrev_b64 v[4:5], 10, v[4:5]
	v_lshl_add_u64 v[6:7], v[132:133], 0, v[4:5]
	v_lshl_add_u64 v[4:5], v[134:135], 0, v[4:5]
	global_load_dwordx4 v[44:47], v[6:7], off
	global_load_dwordx4 v[48:51], v[4:5], off

; __device__ __forceinline__ void gla_unit(const Params& p, const WS& ws, int u, bool dry = false) {
;     ...
;     ebl[0] = BLp[c * 128 + 16 * (2 * w) + lr];
;     ebl[1] = BLp[c * 128 + 16 * (2 * w + 1) + lr];
.LBB0_1649:
	s_or_b64 exec, exec, s[12:13]
	global_load_dword v209, v[140:141], off offset:512
	global_load_dword v242, v[140:141], off offset:576

; __device__ __forceinline__ void gla_unit(const Params& p, const WS& ws, int u, bool dry = false) {
;     ...
; #pragma unroll 1
;   for (int c = 0; c < 33; c += 2) {
;     body(c, qrA, krA, vrA, eblA);
;     if (c + 1 < 33) body(c + 1, qrB, krB, vrB, eblB);
;   }
.LBB0_1663:
	v_lshl_add_u32 v11, s37, 6, v162
	s_waitcnt vmcnt(0)
	v_mov_b32_e32 v242, v179
	v_mov_b32_e32 v209, v204
.LBB0_1664:
	s_add_i32 s37, s37, 2
	s_addk_i32 s92, 0x80
	s_add_i32 s35, s35, 2
	s_cmp_gt_u32 s8, 30
	s_mov_b64 s[8:9], 0x400
	v_lshl_add_u64 v[140:141], v[140:141], 0, s[8:9]
	s_cbranch_scc1 .LBB0_1666
	v_mov_b32_e32 v207, v206
	v_mov_b32_e32 v208, v205
	s_branch .LBB0_1607
.Lgla_skipA:
	s_waitcnt vmcnt(0)
	s_branch .LBB0_1622
